# rs cache across tiles of a row block extended to P3 (both epilogue bodies) and P1, in addition to P7
# speedup vs baseline: 1.0201x; 1.0104x over previous
; #define PG8_STAGE(bufoff, gbase, voff) do { _Pragma("unroll") for (int _i = 0; _i < 2; ++_i) \
;         __builtin_amdgcn_global_load_lds((const unsigned*)((const char*)(gbase) + (voff)[_i]), (LAS unsigned*)(lds + (bufoff) + ldsw + _i * 8192), 16, 0, 0); } while (0)
; #define PG8_WAIT_V(n) asm volatile("s_waitcnt vmcnt(" #n ")" ::: "memory")
; #define PG8_BAR __builtin_amdgcn_s_barrier()
; __device__ __forceinline__ unsigned xb_ld(unsigned* p)              { return __hip_atomic_load(p, __ATOMIC_RELAXED, __HIP_MEMORY_SCOPE_AGENT); }
; template <class Epi>
; __device__ __forceinline__ void gemm_phase(LAS unsigned char* lds, const Gemm g, const StaticOrder& S, const Epi& E) {
;     ...
;     const size_t aslab = g.aslab ? g.aslab : 32 * tstepA;
;     const char* cA = (const char*)g.A + (size_t)(cur.pm >> 5) * aslab + (size_t)(cur.pm & 31) * tstepA; const char* cB = (const char*)g.Bt + (size_t)cur.pn * tstepB;
;     PG8_STAGE(PG8_SB(0, 0), cB, voffB); PG8_STAGE(PG8_SB(0, 1), cB + hstepB, voffB); PG8_STAGE(PG8_SA(0, 0), cA, voffA); PG8_STAGE(PG8_SA(0, 1), cA + hstepA, voffA);
;     if (wr == 1) PG8_BAR;
;     PG8_WAIT_V(2); PG8_BAR;
;     PG8_STAGE(PG8_SB(1, 0), cB + kstep, voffB); PG8_STAGE(PG8_SA(1, 0), cA + kstep, voffA); PG8_STAGE(PG8_SB(1, 1), cB + hstepB + kstep, voffB);
;     PG8_WAIT_V(6); PG8_BAR;
; __global__ void __launch_bounds__(512, 2) mk_fwd(Args a) {
;     ...
;     int loc = ((G & 7) == 0 && G >= 8) ? 1 : 0;
;     { unsigned all = 0u;
; #pragma unroll
;       for (int k = 0; k < 8; ++k) { const unsigned mk = (unsigned)__builtin_amdgcn_readfirstlane(xb_ld(&lbar[LB_CLS(k)])); if (mk == 0u || (mk & (mk - 1u)) != 0u || (all & mk) != 0u) loc = 0; all |= mk; } }
;     const unsigned nloc_l = (unsigned)(G >> 3);
;     ...
;     pg8::StaticOrder S;
;     { pg8::Gemm g{XB, W13_1, M_TOK, 2 * D_FF, D_MODEL, D_MODEL}; S.init(M_TOK, 2 * D_FF, G, bx); pg8::EpiSwiglu<1> E{U, ss1}; pg8::gemm_phase(lds, g, S, E); }
.LBB0_144:
	s_or_b64 exec, exec, s[0:1]
	v_mov_b32_e32 v248, -1
	v_readlane_b32 s0, v235, 7
	v_mov_b32_e32 v129, 0
	v_readlane_b32 s1, v235, 8
	v_mov_b32_e32 v1, 0x904000
	s_waitcnt lgkmcnt(0)
	s_barrier
	v_mov_b32_e32 v8, v196
	s_nop 0
	global_load_dword v0, v129, s[0:1] sc1
	global_load_dword v2, v1, s[72:73] offset:8 sc1
	global_load_dword v3, v1, s[72:73] offset:16 sc1
	global_load_dword v4, v1, s[72:73] offset:24 sc1
	global_load_dword v5, v1, s[72:73] offset:32 sc1
	global_load_dword v6, v1, s[72:73] offset:40 sc1
	global_load_dword v7, v1, s[72:73] offset:48 sc1
	global_load_dword v9, v1, s[72:73] offset:56 sc1
	s_add_u32 s0, s72, 0xc000000
	s_addc_u32 s1, s73, 0
	v_writelane_b32 v235, s0, 44
	s_waitcnt vmcnt(6)
	v_readfirstlane_b32 s39, v2
	v_writelane_b32 v235, s1, 45
	s_waitcnt vmcnt(5)
	v_readfirstlane_b32 s37, v3
	v_readlane_b32 s0, v235, 0
	s_cmpk_lt_i32 s0, 0x1600
	s_cselect_b64 s[2:3], -1, 0
	v_writelane_b32 v235, s2, 46
	s_cmpk_gt_i32 s0, 0x15ff
	v_readfirstlane_b32 s38, v0
	s_waitcnt vmcnt(4)
	v_readfirstlane_b32 s36, v4
	s_waitcnt vmcnt(3)
	v_readfirstlane_b32 s35, v5
	s_waitcnt vmcnt(2)
	v_readfirstlane_b32 s34, v6
	s_waitcnt vmcnt(1)
	v_readfirstlane_b32 s31, v7
	s_waitcnt vmcnt(0)
	v_readfirstlane_b32 s30, v9
	v_readfirstlane_b32 s1, v8
	v_writelane_b32 v235, s3, 47
	s_cbranch_scc1 .LBB0_160
	v_lshlrev_b32_e32 v0, 4, v8
	v_add_u32_e32 v1, 0x2000, v0
	v_ashrrev_i32_e32 v2, 31, v1
	v_lshrrev_b32_e32 v2, 22, v2
	v_add_u32_e32 v2, v1, v2
	v_ashrrev_i32_e32 v9, 10, v2
	v_mul_i32_i24_e32 v2, 0x400, v9
	v_sub_u32_e32 v1, v1, v2
	v_lshrrev_b32_e32 v2, 4, v1
	v_bitop3_b32 v1, v2, v1, 32 bitop3:0x6c
	v_ashrrev_i32_e32 v2, 31, v1
	v_lshrrev_b32_e32 v2, 26, v2
	v_add_u32_e32 v2, v1, v2
	v_lshlrev_b32_e32 v3, 3, v9
	v_ashrrev_i32_e32 v10, 6, v2
	v_and_b32_e32 v3, -16, v3
	v_add_u32_e32 v3, v10, v3
	v_and_b32_e32 v4, 3, v10
	s_mov_b32 s0, 0x1fffe0
	v_lshrrev_b32_e32 v5, 2, v3
	v_lshlrev_b32_e32 v6, 1, v3
	v_and_b32_e32 v2, 0xc0, v2
	v_and_or_b32 v4, v3, s0, v4
	v_and_b32_e32 v5, 4, v5
	v_and_b32_e32 v6, 24, v6
	v_sub_u32_e32 v1, v1, v2
	v_mov_b32_e32 v2, 1
	v_or3_b32 v4, v4, v5, v6
	v_lshlrev_b32_e32 v5, 5, v9
	v_ashrrev_i16_sdwa v1, v2, sext(v1) dst_sel:DWORD dst_unused:UNUSED_PAD src0_sel:DWORD src1_sel:BYTE_0
	v_and_b32_e32 v5, 32, v5
	v_bfe_i32 v11, v1, 0, 16
	v_add_lshl_u32 v1, v5, v11, 1
	v_lshl_add_u32 v130, v4, 11, v1
	v_lshl_add_u32 v132, v3, 11, v1
	v_bfe_i32 v1, v8, 27, 1
	v_lshrrev_b32_e32 v1, 22, v1
	v_add_u32_e32 v1, v0, v1
	v_and_b32_e32 v1, 0xfffffc00, v1
	v_sub_u32_e32 v0, v0, v1
	v_lshrrev_b32_e32 v1, 4, v0
	v_ashrrev_i32_e32 v3, 31, v8
	v_bitop3_b32 v0, v1, v0, 32 bitop3:0x6c
	v_lshrrev_b32_e32 v3, 26, v3
	v_ashrrev_i32_e32 v1, 31, v0
	v_add_u32_e32 v3, v8, v3
	v_lshrrev_b32_e32 v1, 26, v1
	v_ashrrev_i32_e32 v13, 6, v3
	v_add_u32_e32 v1, v0, v1
	v_lshlrev_b32_e32 v3, 3, v13
	v_ashrrev_i32_e32 v12, 6, v1
	v_and_b32_e32 v3, -16, v3
	v_readlane_b32 s3, v235, 0
	v_add_u32_e32 v3, v12, v3
	v_and_b32_e32 v4, 3, v12
	s_ashr_i32 s18, s3, 31
	v_and_or_b32 v4, v3, s0, v4
	s_lshr_b32 s0, s18, 29
	s_add_i32 s0, s3, s0
	s_ashr_i32 s14, s1, 6
	s_ashr_i32 s2, s0, 3
	s_and_b32 s0, s0, -8
	s_ashr_i32 s15, s1, 8
	s_lshl_b32 s40, s14, 10
	s_sub_i32 s0, s3, s0
	s_cmp_lt_i32 s0, 0
	s_movk_i32 s41, 0x2c1
	s_cselect_b32 s3, s41, 0x2c0
	s_mul_i32 s0, s0, s3
	s_add_i32 s0, s0, s2
	s_mul_hi_i32 s2, s0, 0x2e8ba2e9
	s_lshr_b32 s3, s2, 31
	s_ashr_i32 s2, s2, 5
	s_add_i32 s2, s2, s3
	s_lshl_b32 s3, s2, 3
	s_mulk_i32 s2, 0xb0
	s_sub_i32 s0, s0, s2
	s_bfe_u32 s2, s0, 0x3001c
	s_add_i32 s2, s0, s2
	s_and_b32 s8, s2, 0xfff8
	s_sub_i32 s0, s0, s8
	s_sext_i32_i16 s0, s0
	s_add_i32 s33, s3, s0
	s_sext_i32_i16 s0, s2
	s_ashr_i32 s2, s33, 5
	s_ashr_i32 s3, s2, 31
	v_lshrrev_b32_e32 v5, 2, v3
	v_lshlrev_b32_e32 v6, 1, v3
	v_and_b32_e32 v1, 0xc0, v1
	s_lshr_b32 s0, s0, 3
	s_lshl_b64 s[8:9], s[2:3], 24
	s_lshl_b32 s2, s33, 19
	v_and_b32_e32 v5, 4, v5
	v_and_b32_e32 v6, 24, v6
	v_sub_u32_e32 v0, v0, v1
	s_and_b32 s16, s2, 0xf80000
	s_bfe_i64 s[2:3], s[0:1], 0x100000
	v_or3_b32 v4, v4, v5, v6
	v_lshlrev_b32_e32 v5, 5, v13
	v_ashrrev_i16_sdwa v0, v2, sext(v0) dst_sel:DWORD dst_unused:UNUSED_PAD src0_sel:DWORD src1_sel:BYTE_0
	s_lshl_b64 s[2:3], s[2:3], 19
	v_and_b32_e32 v5, 32, v5
	v_bfe_i32 v14, v0, 0, 16
	s_add_u32 s2, s6, s2
	v_add_lshl_u32 v0, v5, v14, 1
	s_addc_u32 s3, s7, s3
	s_add_i32 s42, s40, 0
	v_lshl_add_u32 v128, v4, 11, v0
	s_add_i32 m0, s42, 0x10000
	v_readlane_b32 s20, v235, 38
	global_load_lds_dwordx4 v128, s[2:3]
	s_add_i32 m0, s42, 0x12000
	v_readlane_b32 s21, v235, 39
	s_add_u32 s17, s20, s8
	s_addc_u32 s19, s21, s9
	s_add_u32 s8, s2, 0x40000
	global_load_lds_dwordx4 v130, s[2:3]
	s_addc_u32 s9, s3, 0
	s_add_i32 m0, s42, 0x14000
	v_lshl_add_u32 v134, v3, 11, v0
	global_load_lds_dwordx4 v128, s[8:9]
	s_add_i32 m0, s42, 0x16000
	s_add_u32 s24, s17, s16
	s_addc_u32 s25, s19, 0
	s_add_i32 s43, s42, 0x2000
	global_load_lds_dwordx4 v130, s[8:9]
	s_mov_b32 m0, s42
	s_add_u32 s8, s24, 0x40000
	global_load_lds_dwordx4 v134, s[24:25]
	s_mov_b32 m0, s43
	s_addc_u32 s9, s25, 0
	s_add_i32 s44, s42, 0x4000
	global_load_lds_dwordx4 v132, s[24:25]
	s_mov_b32 m0, s44
	s_add_i32 s45, s42, 0x6000
	global_load_lds_dwordx4 v134, s[8:9]
	s_mov_b32 m0, s45
	v_mov_b32_e32 v131, v129
	global_load_lds_dwordx4 v132, s[8:9]
	v_mov_b32_e32 v135, v129
	v_mov_b32_e32 v133, v129
	s_cmp_eq_u32 s15, 1
	s_mov_b32 s46, 0
	v_lshl_add_u64 v[6:7], s[2:3], 0, v[128:129]
	v_lshl_add_u64 v[2:3], s[2:3], 0, v[130:131]
	s_mov_b32 s47, 0x16000
	v_lshl_add_u64 v[0:1], s[24:25], 0, v[134:135]
	s_cselect_b64 s[8:9], -1, 0
	s_cmp_lg_u32 s15, 1
	v_lshl_add_u64 v[4:5], s[24:25], 0, v[132:133]
	s_cbranch_scc1 .LBB0_147
	s_barrier

; template <int NP> __device__ __forceinline__ void load_rs(const float* ssp, int row0, int fq, float (&rs)[2][4]) {
;     if (NP == 1) {
; #pragma unroll
;         for (int ai = 0; ai < 2; ++ai)
; #pragma unroll
;             for (int m = 0; m < 4; ++m) rs[ai][m] = ssp[row0 + ai * HALF + m * 16];
;     } else {
;         f32x4 p[2][4];
; #pragma unroll
;         for (int ai = 0; ai < 2; ++ai)
; #pragma unroll
;             for (int m = 0; m < 4; ++m) p[ai][m] = *(const f32x4*)(ssp + (size_t)(row0 + ai * HALF + m * 16) * 16 + 4 * fq);
; #pragma unroll
;         for (int ai = 0; ai < 2; ++ai)
; #pragma unroll
;             for (int m = 0; m < 4; ++m) { float s = (p[ai][m][0] + p[ai][m][1]) + (p[ai][m][2] + p[ai][m][3]); s += __shfl_xor(s, 16); s += __shfl_xor(s, 32); rs[ai][m] = s; }
;     }
; #pragma unroll
;     for (int ai = 0; ai < 2; ++ai)
; #pragma unroll
;         for (int m = 0; m < 4; ++m) rs[ai][m] = __builtin_amdgcn_rsqf(rs[ai][m] * (1.0f / D_MODEL) + RMS_EPS);
; }
;     __device__ __forceinline__ void operator()(const f32x4 (&acc)[2][2][4][2], const Unit& u, int wr, int wc, int fr, int fq) const {
;         const int row0 = u.pm * BM + wr * 64 + fr, col0 = u.pn * HALF + wc * 32 + 8 * fq;
;         float rs[2][4]; load_rs<NP>(ssp, row0, fq, rs);
; #pragma unroll
;         for (int ai = 0; ai < 2; ++ai)
; #pragma unroll
;             for (int m = 0; m < 4; ++m) {
;                 const int row = row0 + ai * HALF + m * 16; const float r = rs[ai][m];
;                 const float nrl = r * -1.44269504089f, r2 = r * r;
;                 unsigned pk[4];
; #pragma unroll
;                 for (int q = 0; q < 4; ++q) {
;                     const f32x4 ga = acc[ai][0][m][q >> 1], ua = acc[ai][1][m][q >> 1]; const int e0 = 2 * (q & 1);
;                     const f32x2 g = (f32x2){ga[e0], ga[e0 + 1]}, up = (f32x2){ua[e0], ua[e0 + 1]};
;                     const f32x2 t = g * nrl; f32x2 ex; ex.x = __builtin_amdgcn_exp2f(t.x); ex.y = __builtin_amdgcn_exp2f(t.y);
;                     const f32x2 d = ex + 1.0f; f32x2 rc; rc.x = __builtin_amdgcn_rcpf(d.x); rc.y = __builtin_amdgcn_rcpf(d.y);
;                     const f32x2 o = (g * up) * (rc * r2);
;                     pk[q] = cvt_pk_bf16(o.x, o.y);
;                 }
;                 u32x4 w; w.x = pk[0]; w.y = pk[1]; w.z = pk[2]; w.w = pk[3];
.LBB0_156:
	v_cmp_eq_u32_e32 vcc, s33, v248
	s_cbranch_vccnz rsc_hit_3
	s_lshl_b32 s2, s33, 8
	s_add_i32 s2, s2, s48
	v_or_b32_e32 v144, s2, v146
	v_ashrrev_i32_e32 v145, 31, v144
	v_lshl_add_u64 v[154:155], v[144:145], 2, s[72:73]
	global_load_dword v145, v[154:155], off
	global_load_dword v162, v[154:155], off offset:64
	global_load_dword v163, v[154:155], off offset:128
	global_load_dword v164, v[154:155], off offset:192
	global_load_dword v165, v[154:155], off offset:512
	global_load_dword v166, v[154:155], off offset:576
	global_load_dword v167, v[154:155], off offset:640
	global_load_dword v168, v[154:155], off offset:704
	v_lshl_or_b32 v154, s57, 7, v148
	v_pk_mul_f32 v[156:157], v[108:109], v[120:121]
	s_ashr_i32 s3, s2, 13
	v_pk_mul_f32 v[158:159], v[106:107], v[114:115]
	v_ashrrev_i32_e32 v155, 31, v154
	v_bitop3_b32 v114, s2, v153, v146 bitop3:0xc8
	s_mul_hi_i32 s19, s3, 0x4400000
	s_mul_i32 s3, s3, 0x4400000
	v_readlane_b32 s24, v235, 44
	v_pk_mul_f32 v[160:161], v[104:105], v[112:113]
	v_lshlrev_b64 v[112:113], 1, v[154:155]
	v_mul_u32_u24_e32 v114, 0xb40, v114
	v_readlane_b32 s25, v235, 45
	s_add_u32 s2, s24, s3
	v_lshlrev_b32_e32 v138, 1, v114
	s_addc_u32 s3, s25, s19
	v_lshl_add_u64 v[114:115], s[2:3], 0, v[138:139]
	v_pk_mul_f32 v[124:125], v[116:117], v[124:125]
	v_pk_mul_f32 v[126:127], v[118:119], v[126:127]
	v_pk_mul_f32 v[122:123], v[110:111], v[122:123]
	v_lshl_add_u64 v[114:115], v[114:115], 0, v[112:113]
	v_pk_mul_f32 v[96:97], v[100:101], v[96:97]
	v_pk_mul_f32 v[98:99], v[102:103], v[98:99]
	v_pk_mul_f32 v[88:89], v[92:93], v[88:89]
	v_pk_mul_f32 v[90:91], v[94:95], v[90:91]
	v_pk_mul_f32 v[80:81], v[84:85], v[80:81]
	v_pk_mul_f32 v[82:83], v[86:87], v[82:83]
	v_pk_mul_f32 v[72:73], v[76:77], v[72:73]
	v_pk_mul_f32 v[74:75], v[78:79], v[74:75]
	v_pk_mul_f32 v[64:65], v[68:69], v[64:65]
	v_pk_mul_f32 v[66:67], v[70:71], v[66:67]
	s_mov_b32 s2, 0x43000
	v_pk_mul_f32 v[56:57], v[60:61], v[56:57]
	v_pk_mul_f32 v[58:59], v[62:63], v[58:59]
	v_pk_mul_f32 v[48:49], v[52:53], v[48:49]
	v_pk_mul_f32 v[50:51], v[54:55], v[50:51]
	v_pk_mul_f32 v[40:41], v[44:45], v[40:41]
	v_pk_mul_f32 v[42:43], v[46:47], v[42:43]
	v_pk_mul_f32 v[32:33], v[36:37], v[32:33]
	v_pk_mul_f32 v[34:35], v[38:39], v[34:35]
	v_pk_mul_f32 v[24:25], v[28:29], v[24:25]
	v_pk_mul_f32 v[26:27], v[30:31], v[26:27]
	v_pk_mul_f32 v[16:17], v[20:21], v[16:17]
	v_pk_mul_f32 v[18:19], v[22:23], v[18:19]
	v_pk_mul_f32 v[8:9], v[12:13], v[8:9]
	v_pk_mul_f32 v[10:11], v[14:15], v[10:11]
	v_pk_mul_f32 v[0:1], v[4:5], v[0:1]
	v_pk_mul_f32 v[2:3], v[6:7], v[2:3]
	s_waitcnt vmcnt(0)
	v_fmamk_f32 v120, v145, 0x3a800000, v152
	v_fmamk_f32 v121, v162, 0x3a800000, v152
	v_fmamk_f32 v138, v163, 0x3a800000, v152
	v_fmamk_f32 v145, v164, 0x3a800000, v152
	v_rsq_f32_e32 v164, v120
	s_nop 0
	v_mov_b32_e32 v240, v164
	v_fmamk_f32 v154, v165, 0x3a800000, v152
	v_rsq_f32_e32 v165, v121
	s_nop 0
	v_mov_b32_e32 v241, v165
	v_fmamk_f32 v162, v167, 0x3a800000, v152
	v_rsq_f32_e32 v170, v138
	s_nop 0
	v_mov_b32_e32 v242, v170
	v_mul_f32_e32 v138, 0xbfb8aa3b, v164
	v_fmamk_f32 v163, v168, 0x3a800000, v152
	v_rsq_f32_e32 v121, v162
	s_nop 0
	v_mov_b32_e32 v246, v121
	v_mul_f32_e32 v162, 0xbfb8aa3b, v165
	v_pk_mul_f32 v[116:117], v[116:117], v[138:139] op_sel_hi:[1,0]
	v_pk_mul_f32 v[108:109], v[108:109], v[138:139] op_sel_hi:[1,0]
	v_pk_mul_f32 v[118:119], v[118:119], v[138:139] op_sel_hi:[1,0]
	v_pk_mul_f32 v[110:111], v[110:111], v[138:139] op_sel_hi:[1,0]
	v_pk_mul_f32 v[104:105], v[104:105], v[162:163] op_sel_hi:[1,0]
	v_exp_f32_e32 v116, v116
	v_exp_f32_e32 v117, v117
	v_exp_f32_e32 v108, v108
	v_exp_f32_e32 v109, v109
	v_pk_mul_f32 v[106:107], v[106:107], v[162:163] op_sel_hi:[1,0]
	v_exp_f32_e32 v118, v118
	v_exp_f32_e32 v119, v119
	v_exp_f32_e32 v110, v110
	v_exp_f32_e32 v111, v111
	v_exp_f32_e32 v104, v104
	v_exp_f32_e32 v105, v105
	v_exp_f32_e32 v106, v106
	v_exp_f32_e32 v107, v107
	v_fmamk_f32 v155, v166, 0x3a800000, v152
	v_pk_add_f32 v[116:117], v[116:117], 1.0 op_sel_hi:[1,0]
	v_pk_add_f32 v[108:109], v[108:109], 1.0 op_sel_hi:[1,0]
	v_rsq_f32_e32 v155, v155
	s_nop 0
	v_mov_b32_e32 v245, v155
	v_pk_add_f32 v[118:119], v[118:119], 1.0 op_sel_hi:[1,0]
	v_pk_add_f32 v[110:111], v[110:111], 1.0 op_sel_hi:[1,0]
	v_pk_add_f32 v[104:105], v[104:105], 1.0 op_sel_hi:[1,0]
	v_rcp_f32_e32 v116, v116
	v_rcp_f32_e32 v117, v117
	v_rcp_f32_e32 v108, v108
	v_rcp_f32_e32 v109, v109
	v_pk_add_f32 v[106:107], v[106:107], 1.0 op_sel_hi:[1,0]
	v_rcp_f32_e32 v118, v118
	v_rcp_f32_e32 v119, v119
	v_rcp_f32_e32 v110, v110
	v_rcp_f32_e32 v111, v111
	v_rcp_f32_e32 v104, v104
	v_rcp_f32_e32 v105, v105
	v_rcp_f32_e32 v168, v106
	v_rcp_f32_e32 v169, v107
	v_rsq_f32_e32 v171, v154
	s_nop 0
	v_mov_b32_e32 v244, v171
	v_mul_f32_e32 v154, v164, v164
	v_mul_f32_e32 v164, v165, v165
	v_pk_mul_f32 v[106:107], v[154:155], v[116:117] op_sel_hi:[0,1]
	v_pk_mul_f32 v[108:109], v[154:155], v[108:109] op_sel_hi:[0,1]
	v_pk_mul_f32 v[116:117], v[154:155], v[118:119] op_sel_hi:[0,1]
	v_pk_mul_f32 v[110:111], v[154:155], v[110:111] op_sel_hi:[0,1]
	v_pk_mul_f32 v[104:105], v[164:165], v[104:105] op_sel_hi:[0,1]
	v_pk_mul_f32 v[106:107], v[124:125], v[106:107]
	v_pk_mul_f32 v[108:109], v[156:157], v[108:109]
	v_pk_mul_f32 v[166:167], v[100:101], v[162:163] op_sel_hi:[1,0]
	v_pk_mul_f32 v[116:117], v[126:127], v[116:117]
	v_pk_mul_f32 v[110:111], v[122:123], v[110:111]
	v_pk_mul_f32 v[118:119], v[160:161], v[104:105]
	v_cvt_pk_bf16_f32 v104, v106, v107
	v_cvt_pk_bf16_f32 v105, v116, v117
	v_cvt_pk_bf16_f32 v106, v108, v109
	v_cvt_pk_bf16_f32 v107, v110, v111
	v_pk_mul_f32 v[108:109], v[164:165], v[168:169] op_sel_hi:[0,1]
	global_store_dwordx4 v[114:115], v[104:107], off
	v_pk_mul_f32 v[108:109], v[158:159], v[108:109]
	v_rsq_f32_e32 v145, v145
	s_nop 0
	v_mov_b32_e32 v243, v145
	v_exp_f32_e32 v106, v166
	v_exp_f32_e32 v107, v167
	v_cvt_pk_bf16_f32 v104, v118, v119
	v_cvt_pk_bf16_f32 v105, v108, v109
	v_pk_mul_f32 v[108:109], v[102:103], v[162:163] op_sel_hi:[1,0]
	v_pk_add_f32 v[106:107], v[106:107], 1.0 op_sel_hi:[1,0]
	v_exp_f32_e32 v108, v108
	v_exp_f32_e32 v109, v109
	v_rcp_f32_e32 v106, v106
	v_rcp_f32_e32 v107, v107
	v_rsq_f32_e32 v120, v163
	s_nop 0
	v_mov_b32_e32 v247, v120
	v_mov_b32_e32 v248, s33
	s_branch rsc_join_3
; __device__ __forceinline__ unsigned cvt_pk_bf16(float lo, float hi) { unsigned r; asm volatile("v_cvt_pk_bf16_f32 %0, %1, %2" : "=v"(r) : "v"(lo), "v"(hi)); return r; }
;     __device__ __forceinline__ void operator()(const f32x4 (&acc)[2][2][4][2], const Unit& u, int wr, int wc, int fr, int fq) const {
;     ...
;         float rs[2][4]; load_rs<NP>(ssp, row0, fq, rs);
; #pragma unroll
;         for (int ai = 0; ai < 2; ++ai)
; #pragma unroll
;             for (int m = 0; m < 4; ++m) {
;                 const int row = row0 + ai * HALF + m * 16; const float r = rs[ai][m];
;                 const float nrl = r * -1.44269504089f, r2 = r * r;
;                 unsigned pk[4];
; #pragma unroll
;                 for (int q = 0; q < 4; ++q) {
;                     const f32x4 ga = acc[ai][0][m][q >> 1], ua = acc[ai][1][m][q >> 1]; const int e0 = 2 * (q & 1);
;                     const f32x2 g = (f32x2){ga[e0], ga[e0 + 1]}, up = (f32x2){ua[e0], ua[e0 + 1]};
;                     const f32x2 t = g * nrl; f32x2 ex; ex.x = __builtin_amdgcn_exp2f(t.x); ex.y = __builtin_amdgcn_exp2f(t.y);
;                     const f32x2 d = ex + 1.0f; f32x2 rc; rc.x = __builtin_amdgcn_rcpf(d.x); rc.y = __builtin_amdgcn_rcpf(d.y);
;                     const f32x2 o = (g * up) * (rc * r2);
;                     pk[q] = cvt_pk_bf16(o.x, o.y);
;                 }
;                 u32x4 w; w.x = pk[0]; w.y = pk[1]; w.z = pk[2]; w.w = pk[3];
;                 *(u32x4*)(U + (size_t)(row >> 13) * U_SLAB + (size_t)(row & (SEQ - 1)) * U_PITCH + col0) = w;
rsc_hit_3:
	s_lshl_b32 s2, s33, 8
	s_add_i32 s2, s2, s48
	v_or_b32_e32 v144, s2, v146
	v_lshl_or_b32 v154, s57, 7, v148
	v_pk_mul_f32 v[156:157], v[108:109], v[120:121]
	s_ashr_i32 s3, s2, 13
	v_pk_mul_f32 v[158:159], v[106:107], v[114:115]
	v_ashrrev_i32_e32 v155, 31, v154
	v_bitop3_b32 v114, s2, v153, v146 bitop3:0xc8
	s_mul_hi_i32 s19, s3, 0x4400000
	s_mul_i32 s3, s3, 0x4400000
	v_readlane_b32 s24, v235, 44
	v_pk_mul_f32 v[160:161], v[104:105], v[112:113]
	v_lshlrev_b64 v[112:113], 1, v[154:155]
	v_mul_u32_u24_e32 v114, 0xb40, v114
	v_readlane_b32 s25, v235, 45
	s_add_u32 s2, s24, s3
	v_lshlrev_b32_e32 v138, 1, v114
	s_addc_u32 s3, s25, s19
	v_lshl_add_u64 v[114:115], s[2:3], 0, v[138:139]
	v_pk_mul_f32 v[124:125], v[116:117], v[124:125]
	v_pk_mul_f32 v[126:127], v[118:119], v[126:127]
	v_pk_mul_f32 v[122:123], v[110:111], v[122:123]
	v_lshl_add_u64 v[114:115], v[114:115], 0, v[112:113]
	v_pk_mul_f32 v[96:97], v[100:101], v[96:97]
	v_pk_mul_f32 v[98:99], v[102:103], v[98:99]
	v_pk_mul_f32 v[88:89], v[92:93], v[88:89]
	v_pk_mul_f32 v[90:91], v[94:95], v[90:91]
	v_pk_mul_f32 v[80:81], v[84:85], v[80:81]
	v_pk_mul_f32 v[82:83], v[86:87], v[82:83]
	v_pk_mul_f32 v[72:73], v[76:77], v[72:73]
	v_pk_mul_f32 v[74:75], v[78:79], v[74:75]
	v_pk_mul_f32 v[64:65], v[68:69], v[64:65]
	v_pk_mul_f32 v[66:67], v[70:71], v[66:67]
	s_mov_b32 s2, 0x43000
	v_pk_mul_f32 v[56:57], v[60:61], v[56:57]
	v_pk_mul_f32 v[58:59], v[62:63], v[58:59]
	v_pk_mul_f32 v[48:49], v[52:53], v[48:49]
	v_pk_mul_f32 v[50:51], v[54:55], v[50:51]
	v_pk_mul_f32 v[40:41], v[44:45], v[40:41]
	v_pk_mul_f32 v[42:43], v[46:47], v[42:43]
	v_pk_mul_f32 v[32:33], v[36:37], v[32:33]
	v_pk_mul_f32 v[34:35], v[38:39], v[34:35]
	v_pk_mul_f32 v[24:25], v[28:29], v[24:25]
	v_pk_mul_f32 v[26:27], v[30:31], v[26:27]
	v_pk_mul_f32 v[16:17], v[20:21], v[16:17]
	v_pk_mul_f32 v[18:19], v[22:23], v[18:19]
	v_pk_mul_f32 v[8:9], v[12:13], v[8:9]
	v_pk_mul_f32 v[10:11], v[14:15], v[10:11]
	v_pk_mul_f32 v[0:1], v[4:5], v[0:1]
	v_pk_mul_f32 v[2:3], v[6:7], v[2:3]
	s_waitcnt vmcnt(0)
	v_mov_b32_e32 v164, v240
	s_nop 0
	v_mov_b32_e32 v165, v241
	s_nop 0
	v_mov_b32_e32 v170, v242
	v_mul_f32_e32 v138, 0xbfb8aa3b, v164
	s_nop 0
	v_mov_b32_e32 v121, v246
	v_mul_f32_e32 v162, 0xbfb8aa3b, v165
	v_pk_mul_f32 v[116:117], v[116:117], v[138:139] op_sel_hi:[1,0]
	v_pk_mul_f32 v[108:109], v[108:109], v[138:139] op_sel_hi:[1,0]
	v_pk_mul_f32 v[118:119], v[118:119], v[138:139] op_sel_hi:[1,0]
	v_pk_mul_f32 v[110:111], v[110:111], v[138:139] op_sel_hi:[1,0]
	v_pk_mul_f32 v[104:105], v[104:105], v[162:163] op_sel_hi:[1,0]
	v_exp_f32_e32 v116, v116
	v_exp_f32_e32 v117, v117
	v_exp_f32_e32 v108, v108
	v_exp_f32_e32 v109, v109
	v_pk_mul_f32 v[106:107], v[106:107], v[162:163] op_sel_hi:[1,0]
	v_exp_f32_e32 v118, v118
	v_exp_f32_e32 v119, v119
	v_exp_f32_e32 v110, v110
	v_exp_f32_e32 v111, v111
	v_exp_f32_e32 v104, v104
	v_exp_f32_e32 v105, v105
	v_exp_f32_e32 v106, v106
	v_exp_f32_e32 v107, v107
	s_nop 0
	v_pk_add_f32 v[116:117], v[116:117], 1.0 op_sel_hi:[1,0]
	v_pk_add_f32 v[108:109], v[108:109], 1.0 op_sel_hi:[1,0]
	v_mov_b32_e32 v155, v245
	v_pk_add_f32 v[118:119], v[118:119], 1.0 op_sel_hi:[1,0]
	v_pk_add_f32 v[110:111], v[110:111], 1.0 op_sel_hi:[1,0]
	v_pk_add_f32 v[104:105], v[104:105], 1.0 op_sel_hi:[1,0]
	v_rcp_f32_e32 v116, v116
	v_rcp_f32_e32 v117, v117
	v_rcp_f32_e32 v108, v108
	v_rcp_f32_e32 v109, v109
	v_pk_add_f32 v[106:107], v[106:107], 1.0 op_sel_hi:[1,0]
	v_rcp_f32_e32 v118, v118
	v_rcp_f32_e32 v119, v119
	v_rcp_f32_e32 v110, v110
	v_rcp_f32_e32 v111, v111
	v_rcp_f32_e32 v104, v104
	v_rcp_f32_e32 v105, v105
	v_rcp_f32_e32 v168, v106
	v_rcp_f32_e32 v169, v107
	v_mov_b32_e32 v171, v244
	v_mul_f32_e32 v154, v164, v164
	v_mul_f32_e32 v164, v165, v165
	v_pk_mul_f32 v[106:107], v[154:155], v[116:117] op_sel_hi:[0,1]
	v_pk_mul_f32 v[108:109], v[154:155], v[108:109] op_sel_hi:[0,1]
	v_pk_mul_f32 v[116:117], v[154:155], v[118:119] op_sel_hi:[0,1]
	v_pk_mul_f32 v[110:111], v[154:155], v[110:111] op_sel_hi:[0,1]
	v_pk_mul_f32 v[104:105], v[164:165], v[104:105] op_sel_hi:[0,1]
	v_pk_mul_f32 v[106:107], v[124:125], v[106:107]
	v_pk_mul_f32 v[108:109], v[156:157], v[108:109]
	v_pk_mul_f32 v[166:167], v[100:101], v[162:163] op_sel_hi:[1,0]
	v_pk_mul_f32 v[116:117], v[126:127], v[116:117]
	v_pk_mul_f32 v[110:111], v[122:123], v[110:111]
	v_pk_mul_f32 v[118:119], v[160:161], v[104:105]
	v_cvt_pk_bf16_f32 v104, v106, v107
	v_cvt_pk_bf16_f32 v105, v116, v117
	v_cvt_pk_bf16_f32 v106, v108, v109
	v_cvt_pk_bf16_f32 v107, v110, v111
	v_pk_mul_f32 v[108:109], v[164:165], v[168:169] op_sel_hi:[0,1]
	global_store_dwordx4 v[114:115], v[104:107], off
	v_pk_mul_f32 v[108:109], v[158:159], v[108:109]
	v_mov_b32_e32 v145, v243
	v_exp_f32_e32 v106, v166
	v_exp_f32_e32 v107, v167
	v_cvt_pk_bf16_f32 v104, v118, v119
	v_cvt_pk_bf16_f32 v105, v108, v109
	v_pk_mul_f32 v[108:109], v[102:103], v[162:163] op_sel_hi:[1,0]
	v_pk_add_f32 v[106:107], v[106:107], 1.0 op_sel_hi:[1,0]
	v_exp_f32_e32 v108, v108
	v_exp_f32_e32 v109, v109
	v_rcp_f32_e32 v106, v106
	v_rcp_f32_e32 v107, v107
	v_mov_b32_e32 v120, v247
	s_waitcnt lgkmcnt(0)
; __device__ __forceinline__ unsigned cvt_pk_bf16(float lo, float hi) { unsigned r; asm volatile("v_cvt_pk_bf16_f32 %0, %1, %2" : "=v"(r) : "v"(lo), "v"(hi)); return r; }
;     __device__ __forceinline__ void operator()(const f32x4 (&acc)[2][2][4][2], const Unit& u, int wr, int wc, int fr, int fq) const {
;     ...
;                 for (int q = 0; q < 4; ++q) {
;                     const f32x4 ga = acc[ai][0][m][q >> 1], ua = acc[ai][1][m][q >> 1]; const int e0 = 2 * (q & 1);
;                     const f32x2 g = (f32x2){ga[e0], ga[e0 + 1]}, up = (f32x2){ua[e0], ua[e0 + 1]};
;                     const f32x2 t = g * nrl; f32x2 ex; ex.x = __builtin_amdgcn_exp2f(t.x); ex.y = __builtin_amdgcn_exp2f(t.y);
;                     const f32x2 d = ex + 1.0f; f32x2 rc; rc.x = __builtin_amdgcn_rcpf(d.x); rc.y = __builtin_amdgcn_rcpf(d.y);
;                     const f32x2 o = (g * up) * (rc * r2);
;                     pk[q] = cvt_pk_bf16(o.x, o.y);
;                 }
;                 u32x4 w; w.x = pk[0]; w.y = pk[1]; w.z = pk[2]; w.w = pk[3];
;                 *(u32x4*)(U + (size_t)(row >> 13) * U_SLAB + (size_t)(row & (SEQ - 1)) * U_PITCH + col0) = w;
rsc_join_3:
	v_pk_add_f32 v[100:101], v[108:109], 1.0 op_sel_hi:[1,0]
	v_pk_mul_f32 v[102:103], v[164:165], v[106:107] op_sel_hi:[0,1]
	v_rcp_f32_e32 v100, v100
	v_rcp_f32_e32 v101, v101
	v_pk_mul_f32 v[96:97], v[96:97], v[102:103]
	s_nop 0
	v_cvt_pk_bf16_f32 v106, v96, v97
	v_pk_mul_f32 v[96:97], v[164:165], v[100:101] op_sel_hi:[0,1]
	v_pk_mul_f32 v[96:97], v[98:99], v[96:97]
	v_add_co_u32_e32 v100, vcc, s47, v114
	v_cvt_pk_bf16_f32 v107, v96, v97
	v_mul_f32_e32 v96, 0xbfb8aa3b, v170
	v_pk_mul_f32 v[98:99], v[92:93], v[96:97] op_sel_hi:[1,0]
	v_pk_mul_f32 v[92:93], v[94:95], v[96:97] op_sel_hi:[1,0]
	v_exp_f32_e32 v98, v98
	v_exp_f32_e32 v99, v99
	v_exp_f32_e32 v92, v92
	v_exp_f32_e32 v93, v93
	v_addc_co_u32_e32 v101, vcc, 0, v115, vcc
	v_pk_add_f32 v[98:99], v[98:99], 1.0 op_sel_hi:[1,0]
	v_pk_add_f32 v[92:93], v[92:93], 1.0 op_sel_hi:[1,0]
	v_rcp_f32_e32 v98, v98
	v_rcp_f32_e32 v99, v99
	v_rcp_f32_e32 v92, v92
	v_rcp_f32_e32 v93, v93
	global_store_dwordx4 v[100:101], v[104:107], off offset:2048
	v_mul_f32_e32 v100, v170, v170
	v_pk_mul_f32 v[94:95], v[100:101], v[98:99] op_sel_hi:[0,1]
	v_pk_mul_f32 v[88:89], v[88:89], v[94:95]
	v_pk_mul_f32 v[94:95], v[84:85], v[96:97] op_sel_hi:[1,0]
	v_pk_mul_f32 v[92:93], v[100:101], v[92:93] op_sel_hi:[0,1]
	v_exp_f32_e32 v94, v94
	v_exp_f32_e32 v95, v95
	v_pk_mul_f32 v[90:91], v[90:91], v[92:93]
	v_pk_mul_f32 v[92:93], v[86:87], v[96:97] op_sel_hi:[1,0]
	v_cvt_pk_bf16_f32 v88, v88, v89
	v_cvt_pk_bf16_f32 v89, v90, v91
	v_pk_add_f32 v[90:91], v[94:95], 1.0 op_sel_hi:[1,0]
	v_exp_f32_e32 v92, v92
	v_exp_f32_e32 v93, v93
	v_rcp_f32_e32 v90, v90
	v_rcp_f32_e32 v91, v91
	v_pk_add_f32 v[84:85], v[92:93], 1.0 op_sel_hi:[1,0]
	s_nop 0
	v_rcp_f32_e32 v84, v84
	v_rcp_f32_e32 v85, v85
	v_pk_mul_f32 v[86:87], v[100:101], v[90:91] op_sel_hi:[0,1]
	v_pk_mul_f32 v[80:81], v[80:81], v[86:87]
	s_nop 0
	v_cvt_pk_bf16_f32 v90, v80, v81
	v_pk_mul_f32 v[80:81], v[100:101], v[84:85] op_sel_hi:[0,1]
	v_pk_mul_f32 v[80:81], v[82:83], v[80:81]
	v_add_co_u32_e32 v84, vcc, s55, v114
	v_cvt_pk_bf16_f32 v91, v80, v81
	v_mul_f32_e32 v80, 0xbfb8aa3b, v145
	v_pk_mul_f32 v[82:83], v[76:77], v[80:81] op_sel_hi:[1,0]
	v_pk_mul_f32 v[76:77], v[78:79], v[80:81] op_sel_hi:[1,0]
	v_exp_f32_e32 v82, v82
	v_exp_f32_e32 v83, v83
	v_exp_f32_e32 v76, v76
	v_exp_f32_e32 v77, v77
	v_addc_co_u32_e32 v85, vcc, 0, v115, vcc
	v_pk_add_f32 v[82:83], v[82:83], 1.0 op_sel_hi:[1,0]
	v_pk_add_f32 v[76:77], v[76:77], 1.0 op_sel_hi:[1,0]
	v_rcp_f32_e32 v82, v82
	v_rcp_f32_e32 v83, v83
	v_rcp_f32_e32 v76, v76
	v_rcp_f32_e32 v77, v77
	global_store_dwordx4 v[84:85], v[88:91], off
	v_mul_f32_e32 v84, v145, v145
	v_pk_mul_f32 v[78:79], v[84:85], v[82:83] op_sel_hi:[0,1]
	v_pk_mul_f32 v[72:73], v[72:73], v[78:79]
	v_pk_mul_f32 v[78:79], v[68:69], v[80:81] op_sel_hi:[1,0]
	v_pk_mul_f32 v[76:77], v[84:85], v[76:77] op_sel_hi:[0,1]
	v_exp_f32_e32 v78, v78
	v_exp_f32_e32 v79, v79
	v_pk_mul_f32 v[74:75], v[74:75], v[76:77]
	v_pk_mul_f32 v[76:77], v[70:71], v[80:81] op_sel_hi:[1,0]
	v_cvt_pk_bf16_f32 v72, v72, v73
	v_cvt_pk_bf16_f32 v73, v74, v75
	v_pk_add_f32 v[74:75], v[78:79], 1.0 op_sel_hi:[1,0]
	v_exp_f32_e32 v76, v76
	v_exp_f32_e32 v77, v77
	v_rcp_f32_e32 v74, v74
	v_rcp_f32_e32 v75, v75
	v_pk_add_f32 v[68:69], v[76:77], 1.0 op_sel_hi:[1,0]
	s_nop 0
	v_rcp_f32_e32 v68, v68
	v_rcp_f32_e32 v69, v69
	v_pk_mul_f32 v[70:71], v[84:85], v[74:75] op_sel_hi:[0,1]
	v_pk_mul_f32 v[64:65], v[64:65], v[70:71]
	s_nop 0
	v_cvt_pk_bf16_f32 v74, v64, v65
	v_pk_mul_f32 v[64:65], v[84:85], v[68:69] op_sel_hi:[0,1]
	v_pk_mul_f32 v[64:65], v[66:67], v[64:65]
	v_mul_f32_e32 v68, v171, v171
	v_cvt_pk_bf16_f32 v75, v64, v65
	v_add_co_u32_e32 v64, vcc, s2, v114
	s_mov_b32 s2, 0x4400000
	s_nop 0
	v_addc_co_u32_e32 v65, vcc, 0, v115, vcc
	global_store_dwordx4 v[64:65], v[72:75], off offset:2048
	v_add_u32_e32 v65, 0x80, v144
	v_mul_f32_e32 v64, 0xbfb8aa3b, v171
	v_pk_mul_f32 v[66:67], v[60:61], v[64:65] op_sel_hi:[1,0]
	v_ashrrev_i32_e32 v69, 13, v65
	v_exp_f32_e32 v66, v66
	v_exp_f32_e32 v67, v67
	v_and_b32_e32 v65, 0x1fcf, v65
	v_pk_mul_f32 v[60:61], v[62:63], v[64:65] op_sel_hi:[1,0]
	v_pk_add_f32 v[66:67], v[66:67], 1.0 op_sel_hi:[1,0]
	v_exp_f32_e32 v60, v60
	v_exp_f32_e32 v61, v61
	v_rcp_f32_e32 v66, v66
	v_rcp_f32_e32 v67, v67
	v_pk_add_f32 v[60:61], v[60:61], 1.0 op_sel_hi:[1,0]
	s_nop 0
	v_rcp_f32_e32 v60, v60
	v_rcp_f32_e32 v61, v61
	v_pk_mul_f32 v[62:63], v[68:69], v[66:67] op_sel_hi:[0,1]
	v_pk_mul_f32 v[56:57], v[56:57], v[62:63]
	v_pk_mul_f32 v[62:63], v[52:53], v[64:65] op_sel_hi:[1,0]
	v_pk_mul_f32 v[60:61], v[68:69], v[60:61] op_sel_hi:[0,1]
	v_exp_f32_e32 v62, v62
	v_exp_f32_e32 v63, v63
	v_pk_mul_f32 v[58:59], v[58:59], v[60:61]
	v_pk_mul_f32 v[60:61], v[54:55], v[64:65] op_sel_hi:[1,0]
	v_cvt_pk_bf16_f32 v56, v56, v57
	v_cvt_pk_bf16_f32 v57, v58, v59
	v_pk_add_f32 v[58:59], v[62:63], 1.0 op_sel_hi:[1,0]
	v_exp_f32_e32 v60, v60
	v_exp_f32_e32 v61, v61
	v_rcp_f32_e32 v58, v58
	v_rcp_f32_e32 v59, v59
	v_pk_add_f32 v[52:53], v[60:61], 1.0 op_sel_hi:[1,0]
	s_nop 0
	v_rcp_f32_e32 v52, v52
	v_rcp_f32_e32 v53, v53
	v_pk_mul_f32 v[54:55], v[68:69], v[58:59] op_sel_hi:[0,1]
	v_pk_mul_f32 v[48:49], v[48:49], v[54:55]
	v_mul_f32_e32 v54, v155, v155
	v_cvt_pk_bf16_f32 v58, v48, v49
	v_pk_mul_f32 v[48:49], v[68:69], v[52:53] op_sel_hi:[0,1]
; __device__ __forceinline__ unsigned cvt_pk_bf16(float lo, float hi) { unsigned r; asm volatile("v_cvt_pk_bf16_f32 %0, %1, %2" : "=v"(r) : "v"(lo), "v"(hi)); return r; }
; #define PG8_BAR __builtin_amdgcn_s_barrier()
;     __device__ __forceinline__ void operator()(const f32x4 (&acc)[2][2][4][2], const Unit& u, int wr, int wc, int fr, int fq) const {
;     ...
;                 for (int q = 0; q < 4; ++q) {
;                     const f32x4 ga = acc[ai][0][m][q >> 1], ua = acc[ai][1][m][q >> 1]; const int e0 = 2 * (q & 1);
;                     const f32x2 g = (f32x2){ga[e0], ga[e0 + 1]}, up = (f32x2){ua[e0], ua[e0 + 1]};
;                     const f32x2 t = g * nrl; f32x2 ex; ex.x = __builtin_amdgcn_exp2f(t.x); ex.y = __builtin_amdgcn_exp2f(t.y);
;                     const f32x2 d = ex + 1.0f; f32x2 rc; rc.x = __builtin_amdgcn_rcpf(d.x); rc.y = __builtin_amdgcn_rcpf(d.y);
;                     const f32x2 o = (g * up) * (rc * r2);
;                     pk[q] = cvt_pk_bf16(o.x, o.y);
;                 }
;                 u32x4 w; w.x = pk[0]; w.y = pk[1]; w.z = pk[2]; w.w = pk[3];
;                 *(u32x4*)(U + (size_t)(row >> 13) * U_SLAB + (size_t)(row & (SEQ - 1)) * U_PITCH + col0) = w;
; template <class Epi>
; __device__ __forceinline__ void gemm_phase(LAS unsigned char* lds, const Gemm g, const StaticOrder& S, const Epi& E) {
;     ...
;         if (wr == 0) PG8_BAR;
;         E(acc, cur, wr, wc, fr, fq);
;         if (!has_next) break;
; #pragma unroll
;         for (int a = 0; a < 2; ++a)
; #pragma unroll
;             for (int b = 0; b < 2; ++b)
; #pragma unroll
;                 for (int m = 0; m < 4; ++m)
; #pragma unroll
;                     for (int n = 0; n < 2; ++n) acc[a][b][m][n] = (f32x4){0.f, 0.f, 0.f, 0.f};
;         cur = nxt; cA = nA; cB = nB; ++ui;
;         if (wr == 1) PG8_BAR;
	v_pk_mul_f32 v[48:49], v[50:51], v[48:49]
	v_mul_u32_u24_e32 v50, 0xb40, v65
	v_lshlrev_b32_e32 v138, 1, v50
	v_mul_f32_e32 v50, 0xbfb8aa3b, v155
	v_pk_mul_f32 v[52:53], v[44:45], v[50:51] op_sel_hi:[1,0]
	v_pk_mul_f32 v[44:45], v[46:47], v[50:51] op_sel_hi:[1,0]
	v_exp_f32_e32 v52, v52
	v_exp_f32_e32 v53, v53
	v_exp_f32_e32 v44, v44
	v_exp_f32_e32 v45, v45
	v_cvt_pk_bf16_f32 v59, v48, v49
	v_pk_add_f32 v[52:53], v[52:53], 1.0 op_sel_hi:[1,0]
	v_mov_b64_e32 v[48:49], s[24:25]
	v_rcp_f32_e32 v52, v52
	v_rcp_f32_e32 v53, v53
	v_pk_add_f32 v[44:45], v[44:45], 1.0 op_sel_hi:[1,0]
	v_mad_i64_i32 v[48:49], s[2:3], v69, s2, v[48:49]
	v_rcp_f32_e32 v44, v44
	v_rcp_f32_e32 v45, v45
	v_pk_mul_f32 v[46:47], v[54:55], v[52:53] op_sel_hi:[0,1]
	v_pk_mul_f32 v[40:41], v[40:41], v[46:47]
	v_pk_mul_f32 v[46:47], v[36:37], v[50:51] op_sel_hi:[1,0]
	v_pk_mul_f32 v[44:45], v[54:55], v[44:45] op_sel_hi:[0,1]
	v_exp_f32_e32 v46, v46
	v_exp_f32_e32 v47, v47
	v_pk_mul_f32 v[42:43], v[42:43], v[44:45]
	v_pk_mul_f32 v[44:45], v[38:39], v[50:51] op_sel_hi:[1,0]
	v_lshl_add_u64 v[48:49], v[48:49], 0, v[138:139]
	v_exp_f32_e32 v44, v44
	v_exp_f32_e32 v45, v45
	v_lshl_add_u64 v[48:49], v[48:49], 0, v[112:113]
	global_store_dwordx4 v[48:49], v[56:59], off
	v_cvt_pk_bf16_f32 v40, v40, v41
	v_cvt_pk_bf16_f32 v41, v42, v43
	v_pk_add_f32 v[42:43], v[46:47], 1.0 op_sel_hi:[1,0]
	v_pk_add_f32 v[36:37], v[44:45], 1.0 op_sel_hi:[1,0]
	v_rcp_f32_e32 v42, v42
	v_rcp_f32_e32 v43, v43
	v_rcp_f32_e32 v36, v36
	v_rcp_f32_e32 v37, v37
	v_pk_mul_f32 v[38:39], v[54:55], v[42:43] op_sel_hi:[0,1]
	v_pk_mul_f32 v[32:33], v[32:33], v[38:39]
	s_nop 0
	v_cvt_pk_bf16_f32 v42, v32, v33
	v_pk_mul_f32 v[32:33], v[54:55], v[36:37] op_sel_hi:[0,1]
	v_pk_mul_f32 v[32:33], v[34:35], v[32:33]
	v_add_co_u32_e32 v36, vcc, s47, v48
	v_cvt_pk_bf16_f32 v43, v32, v33
	v_mul_f32_e32 v32, 0xbfb8aa3b, v121
	v_pk_mul_f32 v[34:35], v[28:29], v[32:33] op_sel_hi:[1,0]
	v_pk_mul_f32 v[28:29], v[30:31], v[32:33] op_sel_hi:[1,0]
	v_exp_f32_e32 v34, v34
	v_exp_f32_e32 v35, v35
	v_exp_f32_e32 v28, v28
	v_exp_f32_e32 v29, v29
	v_addc_co_u32_e32 v37, vcc, 0, v49, vcc
	v_pk_add_f32 v[34:35], v[34:35], 1.0 op_sel_hi:[1,0]
	v_pk_add_f32 v[28:29], v[28:29], 1.0 op_sel_hi:[1,0]
	v_rcp_f32_e32 v34, v34
	v_rcp_f32_e32 v35, v35
	v_rcp_f32_e32 v28, v28
	v_rcp_f32_e32 v29, v29
	global_store_dwordx4 v[36:37], v[40:43], off offset:2048
	v_mul_f32_e32 v36, v121, v121
	v_pk_mul_f32 v[30:31], v[36:37], v[34:35] op_sel_hi:[0,1]
	v_pk_mul_f32 v[24:25], v[24:25], v[30:31]
	v_pk_mul_f32 v[30:31], v[20:21], v[32:33] op_sel_hi:[1,0]
	v_pk_mul_f32 v[28:29], v[36:37], v[28:29] op_sel_hi:[0,1]
	v_exp_f32_e32 v30, v30
	v_exp_f32_e32 v31, v31
	v_pk_mul_f32 v[26:27], v[26:27], v[28:29]
	v_pk_mul_f32 v[28:29], v[22:23], v[32:33] op_sel_hi:[1,0]
	v_cvt_pk_bf16_f32 v24, v24, v25
	v_cvt_pk_bf16_f32 v25, v26, v27
	v_pk_add_f32 v[26:27], v[30:31], 1.0 op_sel_hi:[1,0]
	v_exp_f32_e32 v28, v28
	v_exp_f32_e32 v29, v29
	v_rcp_f32_e32 v26, v26
	v_rcp_f32_e32 v27, v27
	v_pk_add_f32 v[20:21], v[28:29], 1.0 op_sel_hi:[1,0]
	s_nop 0
	v_rcp_f32_e32 v20, v20
	v_rcp_f32_e32 v21, v21
	v_pk_mul_f32 v[22:23], v[36:37], v[26:27] op_sel_hi:[0,1]
	v_pk_mul_f32 v[16:17], v[16:17], v[22:23]
	s_nop 0
	v_cvt_pk_bf16_f32 v26, v16, v17
	v_pk_mul_f32 v[16:17], v[36:37], v[20:21] op_sel_hi:[0,1]
	v_pk_mul_f32 v[16:17], v[18:19], v[16:17]
	v_add_co_u32_e32 v20, vcc, s55, v48
	v_cvt_pk_bf16_f32 v27, v16, v17
	v_mul_f32_e32 v16, 0xbfb8aa3b, v120
	v_pk_mul_f32 v[18:19], v[12:13], v[16:17] op_sel_hi:[1,0]
	v_pk_mul_f32 v[12:13], v[14:15], v[16:17] op_sel_hi:[1,0]
	v_exp_f32_e32 v18, v18
	v_exp_f32_e32 v19, v19
	v_exp_f32_e32 v12, v12
	v_exp_f32_e32 v13, v13
	v_addc_co_u32_e32 v21, vcc, 0, v49, vcc
	v_pk_add_f32 v[18:19], v[18:19], 1.0 op_sel_hi:[1,0]
	v_pk_add_f32 v[12:13], v[12:13], 1.0 op_sel_hi:[1,0]
	v_rcp_f32_e32 v18, v18
	v_rcp_f32_e32 v19, v19
	v_rcp_f32_e32 v12, v12
	v_rcp_f32_e32 v13, v13
	global_store_dwordx4 v[20:21], v[24:27], off
	v_mul_f32_e32 v20, v120, v120
	v_pk_mul_f32 v[14:15], v[20:21], v[18:19] op_sel_hi:[0,1]
	v_pk_mul_f32 v[8:9], v[8:9], v[14:15]
	v_pk_mul_f32 v[14:15], v[4:5], v[16:17] op_sel_hi:[1,0]
	v_pk_mul_f32 v[12:13], v[20:21], v[12:13] op_sel_hi:[0,1]
	v_exp_f32_e32 v14, v14
	v_exp_f32_e32 v15, v15
	v_pk_mul_f32 v[10:11], v[10:11], v[12:13]
	v_pk_mul_f32 v[12:13], v[6:7], v[16:17] op_sel_hi:[1,0]
	v_cvt_pk_bf16_f32 v8, v8, v9
	v_cvt_pk_bf16_f32 v9, v10, v11
	v_pk_add_f32 v[10:11], v[14:15], 1.0 op_sel_hi:[1,0]
	v_exp_f32_e32 v12, v12
	v_exp_f32_e32 v13, v13
	v_rcp_f32_e32 v10, v10
	v_rcp_f32_e32 v11, v11
	v_pk_add_f32 v[4:5], v[12:13], 1.0 op_sel_hi:[1,0]
	s_nop 0
	v_rcp_f32_e32 v4, v4
	v_rcp_f32_e32 v5, v5
	v_pk_mul_f32 v[6:7], v[20:21], v[10:11] op_sel_hi:[0,1]
	v_pk_mul_f32 v[0:1], v[0:1], v[6:7]
	s_nop 0
	v_cvt_pk_bf16_f32 v10, v0, v1
	v_pk_mul_f32 v[0:1], v[20:21], v[4:5] op_sel_hi:[0,1]
	v_pk_mul_f32 v[0:1], v[2:3], v[0:1]
	s_nop 0
	v_cvt_pk_bf16_f32 v11, v0, v1
	v_add_co_u32_e32 v0, vcc, 0x43000, v48
	s_nop 1
	v_addc_co_u32_e32 v1, vcc, 0, v49, vcc
	s_andn2_b64 vcc, exec, s[0:1]
	s_mov_b64 s[0:1], -1
	global_store_dwordx4 v[0:1], v[8:11], off offset:2048
	s_cbranch_vccnz .LBB0_149
	s_andn2_b64 vcc, exec, s[8:9]
	s_cbranch_vccnz .LBB0_148
	s_barrier
	s_branch .LBB0_148

; #define PG8_STAGE(bufoff, gbase, voff) do { _Pragma("unroll") for (int _i = 0; _i < 2; ++_i) \
;         __builtin_amdgcn_global_load_lds((const unsigned*)((const char*)(gbase) + (voff)[_i]), (LAS unsigned*)(lds + (bufoff) + ldsw + _i * 8192), 16, 0, 0); } while (0)
; #define PG8_WAIT_V(n) asm volatile("s_waitcnt vmcnt(" #n ")" ::: "memory")
; #define PG8_BAR __builtin_amdgcn_s_barrier()
; template <class Epi>
; __device__ __forceinline__ void gemm_phase(LAS unsigned char* lds, const Gemm g, const StaticOrder& S, const Epi& E) {
;     ...
;     const int wid = __builtin_amdgcn_readfirstlane(tid >> 6), lane = tid & 63, wr = wid >> 2, wc = wid & 3, fr = lane & 15, fq = lane >> 4;
;     const int K = g.K, nt = K / BK, lda = g.lda;
;     unsigned voffA[2], voffB[2];
; #pragma unroll
;     for (int i = 0; i < 2; ++i) { int R, C; stage_rc(tid * 16 + i * 8192, R, C); const int Rb = Epi::PERM ? ((R & ~31) + perm32(R & 31)) : R;
;         voffA[i] = (unsigned)(R * lda + C) * 2u; voffB[i] = (unsigned)(Rb * K + C) * 2u; }
;     const size_t kstep = (size_t)(BK * 2);
;     const size_t hstepA = (size_t)HALF * lda * 2, hstepB = (size_t)HALF * K * 2;
;     const size_t tstepA = 2 * hstepA, tstepB = 2 * hstepB;
;     const unsigned ldsw = (unsigned)wid * 1024u;
;     const int aoff = lds_byte(wr * 64 + fr, fq * 8), boff = lds_byte(wc * 32 + fr, fq * 8);
;     ...
;     Unit cur, nxt; int ui = 0;
;     if (!S.next(0, cur)) return;
;     f32x4 acc[2][2][4][2];
; #pragma unroll
;     for (int a = 0; a < 2; ++a)
; #pragma unroll
;         for (int b = 0; b < 2; ++b)
; #pragma unroll
;             for (int m = 0; m < 4; ++m)
; #pragma unroll
;                 for (int n = 0; n < 2; ++n) acc[a][b][m][n] = (f32x4){0.f, 0.f, 0.f, 0.f};
;     bf16x8 At[4][2], B0[2][2], B1[2][2];
;     const size_t aslab = g.aslab ? g.aslab : 32 * tstepA;
;     const char* cA = (const char*)g.A + (size_t)(cur.pm >> 5) * aslab + (size_t)(cur.pm & 31) * tstepA; const char* cB = (const char*)g.Bt + (size_t)cur.pn * tstepB;
;     PG8_STAGE(PG8_SB(0, 0), cB, voffB); PG8_STAGE(PG8_SB(0, 1), cB + hstepB, voffB); PG8_STAGE(PG8_SA(0, 0), cA, voffA); PG8_STAGE(PG8_SA(0, 1), cA + hstepA, voffA);
;     if (wr == 1) PG8_BAR;
;     PG8_WAIT_V(2); PG8_BAR;
;     PG8_STAGE(PG8_SB(1, 0), cB + kstep, voffB); PG8_STAGE(PG8_SA(1, 0), cA + kstep, voffA); PG8_STAGE(PG8_SB(1, 1), cB + hstepB + kstep, voffB);
;     PG8_WAIT_V(6); PG8_BAR;
.LBB0_370:
	v_mov_b32_e32 v248, -1
	v_mov_b32_e32 v10, v196
	v_readlane_b32 s0, v235, 0
	s_waitcnt lgkmcnt(0)
	s_cmpk_gt_i32 s0, 0x10ff
	v_readfirstlane_b32 s5, v10
	s_cbranch_scc1 .LBB0_390
	v_lshlrev_b32_e32 v0, 4, v10
	v_add_u32_e32 v1, 0x2000, v0
	v_ashrrev_i32_e32 v2, 31, v1
	v_lshrrev_b32_e32 v2, 22, v2
	v_add_u32_e32 v2, v1, v2
	v_ashrrev_i32_e32 v8, 10, v2
	v_mul_i32_i24_e32 v2, 0x400, v8
	v_sub_u32_e32 v1, v1, v2
	v_lshrrev_b32_e32 v2, 4, v1
	v_bitop3_b32 v1, v2, v1, 32 bitop3:0x6c
	v_ashrrev_i32_e32 v2, 31, v1
	v_lshrrev_b32_e32 v2, 26, v2
	v_add_u32_e32 v2, v1, v2
	v_lshlrev_b32_e32 v3, 3, v8
	v_ashrrev_i32_e32 v9, 6, v2
	v_and_b32_e32 v3, -16, v3
	v_add_u32_e32 v3, v9, v3
	v_and_b32_e32 v4, 3, v9
	s_mov_b32 s0, 0x1fffe0
	v_lshrrev_b32_e32 v5, 2, v3
	v_lshlrev_b32_e32 v6, 1, v3
	v_and_b32_e32 v2, 0xc0, v2
	v_and_or_b32 v4, v3, s0, v4
	v_and_b32_e32 v5, 4, v5
	v_and_b32_e32 v6, 24, v6
	v_sub_u32_e32 v1, v1, v2
	v_mov_b32_e32 v2, 1
	v_or3_b32 v4, v4, v5, v6
	v_lshlrev_b32_e32 v5, 5, v8
	v_ashrrev_i16_sdwa v1, v2, sext(v1) dst_sel:DWORD dst_unused:UNUSED_PAD src0_sel:DWORD src1_sel:BYTE_0
	v_and_b32_e32 v5, 32, v5
	v_bfe_i32 v11, v1, 0, 16
	v_add_lshl_u32 v1, v5, v11, 1
	v_lshl_add_u32 v152, v4, 11, v1
	v_lshl_add_u32 v154, v3, 11, v1
	v_bfe_i32 v1, v10, 27, 1
	v_lshrrev_b32_e32 v1, 22, v1
	v_add_u32_e32 v1, v0, v1
	v_and_b32_e32 v1, 0xfffffc00, v1
	v_sub_u32_e32 v0, v0, v1
	v_lshrrev_b32_e32 v1, 4, v0
	v_ashrrev_i32_e32 v3, 31, v10
	v_bitop3_b32 v0, v1, v0, 32 bitop3:0x6c
	v_lshrrev_b32_e32 v3, 26, v3
	v_ashrrev_i32_e32 v1, 31, v0
	v_add_u32_e32 v3, v10, v3
	v_lshrrev_b32_e32 v1, 26, v1
	v_ashrrev_i32_e32 v13, 6, v3
	v_add_u32_e32 v1, v0, v1
	v_lshlrev_b32_e32 v3, 3, v13
	v_ashrrev_i32_e32 v12, 6, v1
	v_and_b32_e32 v3, -16, v3
	v_readlane_b32 s2, v235, 0
	v_add_u32_e32 v3, v12, v3
	v_and_b32_e32 v4, 3, v12
	s_ashr_i32 s16, s2, 31
	v_and_or_b32 v4, v3, s0, v4
	s_lshr_b32 s0, s16, 29
	s_add_i32 s0, s2, s0
	s_ashr_i32 s6, s5, 6
	s_ashr_i32 s1, s0, 3
	s_and_b32 s0, s0, -8
	s_ashr_i32 s8, s5, 8
	s_lshl_b32 s26, s6, 10
	s_sub_i32 s0, s2, s0
	s_cmp_lt_i32 s0, 0
	s_movk_i32 s27, 0x221
	s_cselect_b32 s2, s27, 0x220
	s_mul_i32 s0, s0, s2
	s_add_i32 s0, s0, s1
	s_mul_hi_i32 s1, s0, 0x78787879
	s_lshr_b32 s2, s1, 31
	s_ashr_i32 s1, s1, 6
	s_add_i32 s1, s1, s2
	s_lshl_b32 s2, s1, 3
	s_mulk_i32 s1, 0x88
	s_sub_i32 s0, s0, s1
	s_bfe_u32 s1, s0, 0x3001c
	s_add_i32 s1, s0, s1
	s_and_b32 s3, s1, 0xfff8
	s_sub_i32 s0, s0, s3
	s_sext_i32_i16 s0, s0
	s_add_i32 s33, s2, s0
	s_sext_i32_i16 s0, s1
	v_lshrrev_b32_e32 v5, 2, v3
	v_lshlrev_b32_e32 v6, 1, v3
	v_and_b32_e32 v1, 0xc0, v1
	s_lshr_b32 s4, s0, 3
	s_ashr_i32 s0, s33, 5
	s_lshl_b32 s2, s33, 19
	v_and_b32_e32 v5, 4, v5
	v_and_b32_e32 v6, 24, v6
	v_sub_u32_e32 v0, v0, v1
	s_ashr_i32 s1, s0, 31
	s_and_b32 s7, s2, 0xf80000
	s_bfe_i64 s[2:3], s[4:5], 0x100000
	v_or3_b32 v4, v4, v5, v6
	v_lshlrev_b32_e32 v5, 5, v13
	v_ashrrev_i16_sdwa v0, v2, sext(v0) dst_sel:DWORD dst_unused:UNUSED_PAD src0_sel:DWORD src1_sel:BYTE_0
	s_lshl_b64 s[0:1], s[0:1], 24
	s_lshl_b64 s[2:3], s[2:3], 19
	v_and_b32_e32 v5, 32, v5
	v_bfe_i32 v14, v0, 0, 16
	s_add_u32 s2, s10, s2
	v_add_lshl_u32 v0, v5, v14, 1
	s_addc_u32 s3, s11, s3
	s_add_i32 s28, s26, 0
	v_lshl_add_u32 v156, v4, 11, v0
	s_add_i32 m0, s28, 0x10000
	v_readlane_b32 s18, v235, 38
	global_load_lds_dwordx4 v156, s[2:3]
	s_add_i32 m0, s28, 0x12000
	v_readlane_b32 s19, v235, 39
	s_add_u32 s9, s18, s0
	s_addc_u32 s17, s19, s1
	s_add_u32 s0, s2, 0x40000
	global_load_lds_dwordx4 v152, s[2:3]
	s_addc_u32 s1, s3, 0
	s_add_i32 m0, s28, 0x14000
	v_lshl_add_u32 v158, v3, 11, v0
	global_load_lds_dwordx4 v156, s[0:1]
	s_add_i32 m0, s28, 0x16000
	s_add_u32 s22, s9, s7
	s_addc_u32 s23, s17, 0
	s_add_i32 s29, s28, 0x2000
	global_load_lds_dwordx4 v152, s[0:1]
	s_mov_b32 m0, s28
	s_add_u32 s0, s22, 0x40000
	global_load_lds_dwordx4 v158, s[22:23]
	s_mov_b32 m0, s29
	s_addc_u32 s1, s23, 0
	s_add_i32 s30, s28, 0x4000
	global_load_lds_dwordx4 v154, s[22:23]
	s_mov_b32 m0, s30
	s_add_i32 s31, s28, 0x6000
	global_load_lds_dwordx4 v158, s[0:1]
	s_mov_b32 m0, s31
	v_mov_b32_e32 v161, 0
	global_load_lds_dwordx4 v154, s[0:1]
	v_mov_b32_e32 v157, v161
	v_mov_b32_e32 v153, v161
	v_mov_b32_e32 v159, v161
	v_mov_b32_e32 v155, v161
	s_cmp_eq_u32 s8, 1
	s_mov_b32 s34, 0
	v_lshl_add_u64 v[6:7], s[2:3], 0, v[156:157]
	v_lshl_add_u64 v[4:5], s[2:3], 0, v[152:153]
	v_lshl_add_u64 v[0:1], s[22:23], 0, v[158:159]
	s_cselect_b64 s[0:1], -1, 0
	s_cmp_lg_u32 s8, 1
	v_lshl_add_u64 v[2:3], s[22:23], 0, v[154:155]
	s_cbranch_scc1 .LBB0_373
	s_barrier

; template <int NP> __device__ __forceinline__ void load_rs(const float* ssp, int row0, int fq, float (&rs)[2][4]) {
;     ...
;         f32x4 p[2][4];
; #pragma unroll
;         for (int ai = 0; ai < 2; ++ai)
; #pragma unroll
;             for (int m = 0; m < 4; ++m) p[ai][m] = *(const f32x4*)(ssp + (size_t)(row0 + ai * HALF + m * 16) * 16 + 4 * fq);
; #pragma unroll
;         for (int ai = 0; ai < 2; ++ai)
; #pragma unroll
;             for (int m = 0; m < 4; ++m) { float s = (p[ai][m][0] + p[ai][m][1]) + (p[ai][m][2] + p[ai][m][3]); s += __shfl_xor(s, 16); s += __shfl_xor(s, 32); rs[ai][m] = s; }
;     }
; #pragma unroll
;     for (int ai = 0; ai < 2; ++ai)
; #pragma unroll
;         for (int m = 0; m < 4; ++m) rs[ai][m] = __builtin_amdgcn_rsqf(rs[ai][m] * (1.0f / D_MODEL) + RMS_EPS);
;     __device__ __forceinline__ void operator()(const f32x4 (&acc)[2][2][4][2], const Unit& u, int wr, int wc, int fr, int fq) const {
;         if (u.pn >= 9) body<true>(acc, u, wr, wc, fr, fq); else body<false>(acc, u, wr, wc, fr, fq);
.LBB0_382:
	v_cmp_eq_u32_e32 vcc, s33, v248
	s_cbranch_vccnz rsc_hit_2
	v_lshl_add_u32 v186, s33, 8, v193
	v_or_b32_e32 v184, 16, v186
	v_ashrrev_i32_e32 v187, 31, v186
	v_ashrrev_i32_e32 v185, 31, v184
	v_lshlrev_b64 v[128:129], 6, v[186:187]
	v_lshlrev_b64 v[130:131], 6, v[184:185]
	v_or_b32_e32 v182, 32, v186
	v_or_b32_e32 v180, 48, v186
	v_lshl_add_u64 v[128:129], v[162:163], 0, v[128:129]
	v_lshl_add_u64 v[130:131], v[162:163], 0, v[130:131]
	v_ashrrev_i32_e32 v183, 31, v182
	v_ashrrev_i32_e32 v181, 31, v180
	global_load_dwordx4 v[148:151], v[128:129], off
	global_load_dwordx4 v[204:207], v[130:131], off
	v_lshlrev_b64 v[128:129], 6, v[182:183]
	v_lshlrev_b64 v[130:131], 6, v[180:181]
	v_add_u32_e32 v178, 0x80, v186
	v_add_u32_e32 v176, 0x90, v186
	v_lshl_add_u64 v[128:129], v[162:163], 0, v[128:129]
	v_lshl_add_u64 v[130:131], v[162:163], 0, v[130:131]
	v_ashrrev_i32_e32 v179, 31, v178
	v_ashrrev_i32_e32 v177, 31, v176
	global_load_dwordx4 v[208:211], v[128:129], off
	global_load_dwordx4 v[140:143], v[130:131], off
	v_lshlrev_b64 v[128:129], 6, v[178:179]
	v_lshlrev_b64 v[130:131], 6, v[176:177]
	v_add_u32_e32 v174, 0xa0, v186
	v_add_u32_e32 v170, 0xb0, v186
	v_lshl_add_u64 v[128:129], v[162:163], 0, v[128:129]
	v_lshl_add_u64 v[130:131], v[162:163], 0, v[130:131]
	v_ashrrev_i32_e32 v175, 31, v174
	v_ashrrev_i32_e32 v171, 31, v170
	global_load_dwordx4 v[144:147], v[128:129], off
	global_load_dwordx4 v[132:135], v[130:131], off
	v_lshlrev_b64 v[128:129], 6, v[174:175]
	v_lshlrev_b64 v[130:131], 6, v[170:171]
	v_lshl_add_u64 v[128:129], v[162:163], 0, v[128:129]
	v_lshl_add_u64 v[130:131], v[162:163], 0, v[130:131]
	global_load_dwordx4 v[136:139], v[128:129], off
	s_nop 0
	global_load_dwordx4 v[128:131], v[130:131], off
	v_and_b32_e32 v172, 64, v201
	v_xor_b32_e32 v171, 16, v201
	v_add_u32_e32 v172, 64, v172
	v_xor_b32_e32 v173, 32, v201
	v_cmp_lt_i32_e32 vcc, v171, v172
	s_cmp_lt_i32 s43, 9
	v_lshl_or_b32 v160, s43, 8, v197
	v_cndmask_b32_e32 v171, v201, v171, vcc
	v_cmp_lt_i32_e32 vcc, v173, v172
	v_lshlrev_b32_e32 v175, 2, v171
	s_waitcnt vmcnt(0)
	v_add_f32_e32 v148, v148, v149
	v_add_f32_e32 v149, v150, v151
	v_cndmask_b32_e32 v172, v201, v173, vcc
	v_add_f32_e32 v177, v148, v149
	v_add_f32_e32 v148, v204, v205
	v_add_f32_e32 v149, v206, v207
	v_lshlrev_b32_e32 v171, 2, v172
	v_add_f32_e32 v179, v148, v149
	v_add_f32_e32 v150, v208, v209
	v_add_f32_e32 v151, v210, v211
	v_add_f32_e32 v181, v150, v151
	s_cbranch_scc0 .LBB0_384
	v_mov_b32_e32 v236, v177
	v_mov_b32_e32 v237, v177
	s_nop 1
	v_permlane16_swap_b32_e32 v236, v237
	v_cndmask_b32_e64 v150, v237, v236, s[98:99]
	v_mov_b32_e32 v236, v179
	v_mov_b32_e32 v237, v179
	s_nop 1
	v_permlane16_swap_b32_e32 v236, v237
	v_cndmask_b32_e64 v151, v237, v236, s[98:99]
	v_mov_b32_e32 v148, v141
	v_mov_b32_e32 v149, v142
	v_mov_b32_e32 v236, v181
	v_mov_b32_e32 v237, v181
	s_nop 1
	v_permlane16_swap_b32_e32 v236, v237
	v_cndmask_b32_e64 v172, v237, v236, s[98:99]
	s_waitcnt lgkmcnt(2)
	v_add_f32_e32 v150, v177, v150
	v_mov_b32_e32 v236, v150
	v_mov_b32_e32 v237, v150
	s_nop 1
	v_permlane32_swap_b32_e32 v236, v237
	v_cndmask_b32_e64 v173, v237, v236, s[100:101]
	s_waitcnt lgkmcnt(2)
	v_add_f32_e32 v183, v179, v151
	v_mov_b32_e32 v151, v143
	v_mov_b32_e32 v236, v183
	v_mov_b32_e32 v237, v183
	s_nop 1
	v_permlane32_swap_b32_e32 v236, v237
	v_cndmask_b32_e64 v185, v237, v236, s[100:101]
	s_waitcnt lgkmcnt(2)
	v_add_f32_e32 v172, v181, v172
	s_waitcnt lgkmcnt(1)
	v_add_f32_e32 v173, v150, v173
	v_mov_b32_e32 v150, v140
	v_pk_add_f32 v[148:149], v[148:149], v[150:151]
	v_mov_b32_e32 v150, v144
	v_add_f32_e32 v188, v148, v149
	v_mov_b32_e32 v148, v145
	v_mov_b32_e32 v149, v146
	v_mov_b32_e32 v151, v147
	v_pk_add_f32 v[148:149], v[148:149], v[150:151]
	v_mov_b32_e32 v236, v188
	v_mov_b32_e32 v237, v188
	s_nop 1
	v_permlane16_swap_b32_e32 v236, v237
	v_cndmask_b32_e64 v190, v237, v236, s[98:99]
	v_add_f32_e32 v148, v148, v149
	v_mov_b32_e32 v236, v148
	v_mov_b32_e32 v237, v148
	s_nop 1
	v_permlane16_swap_b32_e32 v236, v237
	v_cndmask_b32_e64 v149, v237, v236, s[98:99]
	s_waitcnt lgkmcnt(2)
	v_add_f32_e32 v183, v183, v185
	v_mov_b32_e32 v150, v132
	s_waitcnt lgkmcnt(1)
	v_add_f32_e32 v185, v188, v190
	v_mov_b32_e32 v151, v135
	s_waitcnt lgkmcnt(0)
	v_add_f32_e32 v188, v148, v149
	v_mov_b32_e32 v148, v133
	v_mov_b32_e32 v149, v134
	v_pk_add_f32 v[148:149], v[148:149], v[150:151]
	v_mov_b32_e32 v150, v136
	v_add_f32_e32 v191, v148, v149
	v_mov_b32_e32 v148, v137
	v_mov_b32_e32 v149, v138
	v_mov_b32_e32 v151, v139
	v_pk_add_f32 v[148:149], v[148:149], v[150:151]
	v_mov_b32_e32 v150, v128
	v_add_f32_e32 v194, v148, v149
	v_mov_b32_e32 v148, v129
	v_mov_b32_e32 v149, v130
	v_mov_b32_e32 v151, v131
	v_pk_add_f32 v[148:149], v[148:149], v[150:151]
	v_mov_b32_e32 v236, v172
	v_mov_b32_e32 v237, v172
	s_nop 1
	v_permlane32_swap_b32_e32 v236, v237
	v_cndmask_b32_e64 v187, v237, v236, s[100:101]
	v_add_f32_e32 v148, v148, v149
	v_mov_b32_e32 v236, v148
	v_mov_b32_e32 v237, v148
	s_nop 1
	v_permlane16_swap_b32_e32 v236, v237
	v_cndmask_b32_e64 v149, v237, v236, s[98:99]
	v_mov_b32_e32 v236, v191
	v_mov_b32_e32 v237, v191
	s_nop 1
	v_permlane16_swap_b32_e32 v236, v237
	v_cndmask_b32_e64 v192, v237, v236, s[98:99]
	v_mov_b32_e32 v236, v194
	v_mov_b32_e32 v237, v194
	s_nop 1
	v_permlane16_swap_b32_e32 v236, v237
	v_cndmask_b32_e64 v203, v237, v236, s[98:99]
	s_waitcnt lgkmcnt(3)
	v_add_f32_e32 v172, v172, v187
	v_mov_b32_e32 v236, v185
	v_mov_b32_e32 v237, v185
	s_nop 1
	v_permlane32_swap_b32_e32 v236, v237
	v_cndmask_b32_e64 v187, v237, v236, s[100:101]
	s_waitcnt lgkmcnt(3)
; __device__ __forceinline__ unsigned cvt_pk_bf16(float lo, float hi) { unsigned r; asm volatile("v_cvt_pk_bf16_f32 %0, %1, %2" : "=v"(r) : "v"(lo), "v"(hi)); return r; }
; template <int NP> __device__ __forceinline__ void load_rs(const float* ssp, int row0, int fq, float (&rs)[2][4]) {
;     ...
;             for (int m = 0; m < 4; ++m) { float s = (p[ai][m][0] + p[ai][m][1]) + (p[ai][m][2] + p[ai][m][3]); s += __shfl_xor(s, 16); s += __shfl_xor(s, 32); rs[ai][m] = s; }
;     }
; #pragma unroll
;     for (int ai = 0; ai < 2; ++ai)
; #pragma unroll
;         for (int m = 0; m < 4; ++m) rs[ai][m] = __builtin_amdgcn_rsqf(rs[ai][m] * (1.0f / D_MODEL) + RMS_EPS);
;     template <bool GATE> __device__ __forceinline__ void body(const f32x4 (&acc)[2][2][4][2], const Unit& u, int wr, int wc, int fr, int fq) const {
;     ...
;                 const int row = row0 + ai * HALF + m * 16; const float r = rs[ai][m], nrl = r * -1.44269504089f;
; #pragma unroll
;                 for (int bj = 0; bj < 2; ++bj) {
;                     unsigned pk[4];
; #pragma unroll
;                     for (int q = 0; q < 4; ++q) {
;                         const f32x4 va = acc[ai][bj][m][q >> 1]; const int e0 = 2 * (q & 1);
;                         const f32x2 v = (f32x2){va[e0], va[e0 + 1]};
;                         f32x2 o;
;                         if (GATE) { const f32x2 t = v * nrl; f32x2 ex; ex.x = __builtin_amdgcn_exp2f(t.x); ex.y = __builtin_amdgcn_exp2f(t.y);
;                             const f32x2 d = ex + 1.0f; o.x = __builtin_amdgcn_rcpf(d.x); o.y = __builtin_amdgcn_rcpf(d.y); }
;                         else o = v * r;
;                         pk[q] = cvt_pk_bf16(o.x, o.y);
;                     }
;                     u32x4 w; w.x = pk[0]; w.y = pk[1]; w.z = pk[2]; w.w = pk[3];
;                     *(u32x4*)(P + (size_t)row * PITCH + col0 + bj * HALF) = w;
	v_add_f32_e32 v148, v148, v149
	v_mov_b32_e32 v236, v148
	v_mov_b32_e32 v237, v148
	s_nop 1
	v_permlane32_swap_b32_e32 v236, v237
	v_cndmask_b32_e64 v149, v237, v236, s[100:101]
	v_mov_b32_e32 v236, v188
	v_mov_b32_e32 v237, v188
	s_nop 1
	v_permlane32_swap_b32_e32 v236, v237
	v_cndmask_b32_e64 v190, v237, v236, s[100:101]
	s_waitcnt lgkmcnt(4)
	v_add_f32_e32 v150, v191, v192
	v_mov_b32_e32 v236, v150
	v_mov_b32_e32 v237, v150
	s_nop 1
	v_permlane32_swap_b32_e32 v236, v237
	v_cndmask_b32_e64 v151, v237, v236, s[100:101]
	s_waitcnt lgkmcnt(4)
	v_add_f32_e32 v191, v194, v203
	v_mov_b32_e32 v236, v191
	v_mov_b32_e32 v237, v191
	s_nop 1
	v_permlane32_swap_b32_e32 v236, v237
	v_cndmask_b32_e64 v192, v237, v236, s[100:101]
	s_waitcnt lgkmcnt(3)
	v_add_f32_e32 v148, v148, v149
	v_fmamk_f32 v149, v173, 0x3a800000, v202
	v_rsq_f32_e32 v208, v149
	s_nop 0
	v_mov_b32_e32 v240, v208
	v_fmamk_f32 v149, v183, 0x3a800000, v202
	v_add_f32_e32 v185, v185, v187
	v_rsq_f32_e32 v210, v149
	s_nop 0
	v_mov_b32_e32 v241, v210
	v_fmamk_f32 v149, v172, 0x3a800000, v202
	s_waitcnt lgkmcnt(2)
	v_add_f32_e32 v187, v188, v190
	v_rsq_f32_e32 v212, v149
	s_nop 0
	v_mov_b32_e32 v242, v212
	v_fmamk_f32 v149, v185, 0x3a800000, v202
	s_waitcnt lgkmcnt(1)
	v_add_f32_e32 v150, v150, v151
	v_rsq_f32_e32 v214, v149
	s_nop 0
	v_mov_b32_e32 v243, v214
	v_fmamk_f32 v149, v187, 0x3a800000, v202
	s_waitcnt lgkmcnt(0)
	v_add_f32_e32 v151, v191, v192
	v_rsq_f32_e32 v194, v149
	s_nop 0
	v_mov_b32_e32 v244, v194
	v_fmamk_f32 v149, v150, 0x3a800000, v202
	v_rsq_f32_e32 v192, v149
	s_nop 0
	v_mov_b32_e32 v245, v192
	v_fmamk_f32 v149, v151, 0x3a800000, v202
	v_fmamk_f32 v148, v148, 0x3a800000, v202
	v_rsq_f32_e32 v190, v149
	s_nop 0
	v_mov_b32_e32 v246, v190
	v_rsq_f32_e32 v188, v148
	s_nop 0
	v_mov_b32_e32 v247, v188
	v_mov_b32_e32 v248, s33
rsc_joina_2:
	v_pk_mul_f32 v[148:149], v[124:125], v[208:209] op_sel_hi:[1,0]
	v_readlane_b32 s2, v235, 44
	v_cvt_pk_bf16_f32 v204, v148, v149
	v_pk_mul_f32 v[148:149], v[126:127], v[208:209] op_sel_hi:[1,0]
	v_readlane_b32 s3, v235, 45
	v_cvt_pk_bf16_f32 v205, v148, v149
	v_pk_mul_f32 v[148:149], v[120:121], v[208:209] op_sel_hi:[1,0]
	v_ashrrev_i32_e32 v173, 31, v160
	v_cvt_pk_bf16_f32 v206, v148, v149
	v_pk_mul_f32 v[148:149], v[122:123], v[208:209] op_sel_hi:[1,0]
	v_mov_b32_e32 v172, v160
	v_cvt_pk_bf16_f32 v207, v148, v149
	v_mov_b64_e32 v[148:149], s[2:3]
	v_mad_i64_i32 v[216:217], s[2:3], v186, s41, v[148:149]
	v_lshlrev_b64 v[150:151], 1, v[172:173]
	v_lshl_add_u64 v[216:217], v[216:217], 0, v[150:151]
	global_store_dwordx4 v[216:217], v[204:207], off
	s_nop 1
	v_pk_mul_f32 v[204:205], v[116:117], v[208:209] op_sel_hi:[1,0]
	v_pk_mul_f32 v[206:207], v[118:119], v[208:209] op_sel_hi:[1,0]
	v_cvt_pk_bf16_f32 v204, v204, v205
	s_nop 0
	v_cvt_pk_bf16_f32 v205, v206, v207
	v_pk_mul_f32 v[206:207], v[112:113], v[208:209] op_sel_hi:[1,0]
	v_pk_mul_f32 v[208:209], v[114:115], v[208:209] op_sel_hi:[1,0]
	v_cvt_pk_bf16_f32 v206, v206, v207
	s_nop 0
	v_cvt_pk_bf16_f32 v207, v208, v209
	global_store_dwordx4 v[216:217], v[204:207], off offset:256
	v_pk_mul_f32 v[208:209], v[106:107], v[210:211] op_sel_hi:[1,0]
	s_nop 0
	v_pk_mul_f32 v[204:205], v[108:109], v[210:211] op_sel_hi:[1,0]
	v_pk_mul_f32 v[206:207], v[110:111], v[210:211] op_sel_hi:[1,0]
	v_cvt_pk_bf16_f32 v204, v204, v205
	s_nop 0
	v_cvt_pk_bf16_f32 v205, v206, v207
	v_pk_mul_f32 v[206:207], v[104:105], v[210:211] op_sel_hi:[1,0]
	s_nop 0
	v_cvt_pk_bf16_f32 v206, v206, v207
	v_cvt_pk_bf16_f32 v207, v208, v209
	v_mad_i64_i32 v[208:209], s[2:3], v184, s41, v[148:149]
	v_lshl_add_u64 v[208:209], v[208:209], 0, v[150:151]
	global_store_dwordx4 v[208:209], v[204:207], off
	s_nop 1
	v_pk_mul_f32 v[204:205], v[100:101], v[210:211] op_sel_hi:[1,0]
	v_pk_mul_f32 v[206:207], v[102:103], v[210:211] op_sel_hi:[1,0]
	v_cvt_pk_bf16_f32 v204, v204, v205
	s_nop 0
	v_cvt_pk_bf16_f32 v205, v206, v207
	v_pk_mul_f32 v[206:207], v[96:97], v[210:211] op_sel_hi:[1,0]
	v_pk_mul_f32 v[210:211], v[98:99], v[210:211] op_sel_hi:[1,0]
	v_cvt_pk_bf16_f32 v206, v206, v207
	s_nop 0
	v_cvt_pk_bf16_f32 v207, v210, v211
	global_store_dwordx4 v[208:209], v[204:207], off offset:256
	v_pk_mul_f32 v[208:209], v[90:91], v[212:213] op_sel_hi:[1,0]
	v_pk_mul_f32 v[210:211], v[82:83], v[212:213] op_sel_hi:[1,0]
	v_pk_mul_f32 v[204:205], v[92:93], v[212:213] op_sel_hi:[1,0]
	v_pk_mul_f32 v[206:207], v[94:95], v[212:213] op_sel_hi:[1,0]
	v_cvt_pk_bf16_f32 v204, v204, v205
	s_nop 0
	v_cvt_pk_bf16_f32 v205, v206, v207
	v_pk_mul_f32 v[206:207], v[88:89], v[212:213] op_sel_hi:[1,0]
	s_nop 0
	v_cvt_pk_bf16_f32 v206, v206, v207
	v_cvt_pk_bf16_f32 v207, v208, v209
	v_mad_i64_i32 v[208:209], s[2:3], v182, s41, v[148:149]
	v_lshl_add_u64 v[208:209], v[208:209], 0, v[150:151]
	global_store_dwordx4 v[208:209], v[204:207], off
	s_nop 1
	v_pk_mul_f32 v[204:205], v[84:85], v[212:213] op_sel_hi:[1,0]
	v_pk_mul_f32 v[206:207], v[86:87], v[212:213] op_sel_hi:[1,0]
	v_cvt_pk_bf16_f32 v204, v204, v205
	s_nop 0
	v_cvt_pk_bf16_f32 v205, v206, v207
	v_pk_mul_f32 v[206:207], v[80:81], v[212:213] op_sel_hi:[1,0]
	s_nop 0
	v_cvt_pk_bf16_f32 v206, v206, v207
	v_cvt_pk_bf16_f32 v207, v210, v211
	global_store_dwordx4 v[208:209], v[204:207], off offset:256
	v_pk_mul_f32 v[208:209], v[74:75], v[214:215] op_sel_hi:[1,0]
; __device__ __forceinline__ unsigned cvt_pk_bf16(float lo, float hi) { unsigned r; asm volatile("v_cvt_pk_bf16_f32 %0, %1, %2" : "=v"(r) : "v"(lo), "v"(hi)); return r; }
;     template <bool GATE> __device__ __forceinline__ void body(const f32x4 (&acc)[2][2][4][2], const Unit& u, int wr, int wc, int fr, int fq) const {
;     ...
;                 const int row = row0 + ai * HALF + m * 16; const float r = rs[ai][m], nrl = r * -1.44269504089f;
; #pragma unroll
;                 for (int bj = 0; bj < 2; ++bj) {
;                     unsigned pk[4];
; #pragma unroll
;                     for (int q = 0; q < 4; ++q) {
;                         const f32x4 va = acc[ai][bj][m][q >> 1]; const int e0 = 2 * (q & 1);
;                         const f32x2 v = (f32x2){va[e0], va[e0 + 1]};
;                         f32x2 o;
;                         if (GATE) { const f32x2 t = v * nrl; f32x2 ex; ex.x = __builtin_amdgcn_exp2f(t.x); ex.y = __builtin_amdgcn_exp2f(t.y);
;                             const f32x2 d = ex + 1.0f; o.x = __builtin_amdgcn_rcpf(d.x); o.y = __builtin_amdgcn_rcpf(d.y); }
;                         else o = v * r;
;                         pk[q] = cvt_pk_bf16(o.x, o.y);
;                     }
;                     u32x4 w; w.x = pk[0]; w.y = pk[1]; w.z = pk[2]; w.w = pk[3];
;                     *(u32x4*)(P + (size_t)row * PITCH + col0 + bj * HALF) = w;
	v_pk_mul_f32 v[210:211], v[66:67], v[214:215] op_sel_hi:[1,0]
	v_pk_mul_f32 v[204:205], v[76:77], v[214:215] op_sel_hi:[1,0]
	v_pk_mul_f32 v[206:207], v[78:79], v[214:215] op_sel_hi:[1,0]
	v_cvt_pk_bf16_f32 v204, v204, v205
	s_nop 0
	v_cvt_pk_bf16_f32 v205, v206, v207
	v_pk_mul_f32 v[206:207], v[72:73], v[214:215] op_sel_hi:[1,0]
	s_nop 0
	v_cvt_pk_bf16_f32 v206, v206, v207
	v_cvt_pk_bf16_f32 v207, v208, v209
	v_mad_i64_i32 v[208:209], s[2:3], v180, s41, v[148:149]
	v_lshl_add_u64 v[208:209], v[208:209], 0, v[150:151]
	global_store_dwordx4 v[208:209], v[204:207], off
	s_nop 1
	v_pk_mul_f32 v[204:205], v[68:69], v[214:215] op_sel_hi:[1,0]
	v_pk_mul_f32 v[206:207], v[70:71], v[214:215] op_sel_hi:[1,0]
	v_cvt_pk_bf16_f32 v204, v204, v205
	s_nop 0
	v_cvt_pk_bf16_f32 v205, v206, v207
	v_pk_mul_f32 v[206:207], v[64:65], v[214:215] op_sel_hi:[1,0]
	s_nop 0
	v_cvt_pk_bf16_f32 v206, v206, v207
	v_cvt_pk_bf16_f32 v207, v210, v211
	global_store_dwordx4 v[208:209], v[204:207], off offset:256
	v_pk_mul_f32 v[208:209], v[58:59], v[194:195] op_sel_hi:[1,0]
	v_pk_mul_f32 v[210:211], v[50:51], v[194:195] op_sel_hi:[1,0]
	v_pk_mul_f32 v[204:205], v[60:61], v[194:195] op_sel_hi:[1,0]
	v_pk_mul_f32 v[206:207], v[62:63], v[194:195] op_sel_hi:[1,0]
	v_cvt_pk_bf16_f32 v204, v204, v205
	s_nop 0
	v_cvt_pk_bf16_f32 v205, v206, v207
	v_pk_mul_f32 v[206:207], v[56:57], v[194:195] op_sel_hi:[1,0]
	s_nop 0
	v_cvt_pk_bf16_f32 v206, v206, v207
	v_cvt_pk_bf16_f32 v207, v208, v209
	v_mad_i64_i32 v[208:209], s[2:3], v178, s41, v[148:149]
	v_lshl_add_u64 v[208:209], v[208:209], 0, v[150:151]
	global_store_dwordx4 v[208:209], v[204:207], off
	s_nop 1
	v_pk_mul_f32 v[204:205], v[52:53], v[194:195] op_sel_hi:[1,0]
	v_pk_mul_f32 v[206:207], v[54:55], v[194:195] op_sel_hi:[1,0]
	v_cvt_pk_bf16_f32 v204, v204, v205
	s_nop 0
	v_cvt_pk_bf16_f32 v205, v206, v207
	v_pk_mul_f32 v[206:207], v[48:49], v[194:195] op_sel_hi:[1,0]
	s_nop 0
	v_cvt_pk_bf16_f32 v206, v206, v207
	v_cvt_pk_bf16_f32 v207, v210, v211
	global_store_dwordx4 v[208:209], v[204:207], off offset:256
	v_pk_mul_f32 v[208:209], v[42:43], v[192:193] op_sel_hi:[1,0]
	v_pk_mul_f32 v[210:211], v[34:35], v[192:193] op_sel_hi:[1,0]
	v_pk_mul_f32 v[204:205], v[44:45], v[192:193] op_sel_hi:[1,0]
	v_pk_mul_f32 v[206:207], v[46:47], v[192:193] op_sel_hi:[1,0]
	v_cvt_pk_bf16_f32 v204, v204, v205
	s_nop 0
	v_cvt_pk_bf16_f32 v205, v206, v207
	v_pk_mul_f32 v[206:207], v[40:41], v[192:193] op_sel_hi:[1,0]
	s_nop 0
	v_cvt_pk_bf16_f32 v206, v206, v207
	v_cvt_pk_bf16_f32 v207, v208, v209
	v_mad_i64_i32 v[208:209], s[2:3], v176, s41, v[148:149]
	v_lshl_add_u64 v[208:209], v[208:209], 0, v[150:151]
	global_store_dwordx4 v[208:209], v[204:207], off
	s_nop 1
	v_pk_mul_f32 v[204:205], v[36:37], v[192:193] op_sel_hi:[1,0]
	v_pk_mul_f32 v[206:207], v[38:39], v[192:193] op_sel_hi:[1,0]
	v_cvt_pk_bf16_f32 v204, v204, v205
	s_nop 0
	v_cvt_pk_bf16_f32 v205, v206, v207
	v_pk_mul_f32 v[206:207], v[32:33], v[192:193] op_sel_hi:[1,0]
	s_nop 0
	v_cvt_pk_bf16_f32 v206, v206, v207
	v_cvt_pk_bf16_f32 v207, v210, v211
	global_store_dwordx4 v[208:209], v[204:207], off offset:256
	v_pk_mul_f32 v[208:209], v[26:27], v[190:191] op_sel_hi:[1,0]
	s_nop 0
	v_pk_mul_f32 v[204:205], v[28:29], v[190:191] op_sel_hi:[1,0]
	v_pk_mul_f32 v[206:207], v[30:31], v[190:191] op_sel_hi:[1,0]
	v_cvt_pk_bf16_f32 v204, v204, v205
	s_nop 0
	v_cvt_pk_bf16_f32 v205, v206, v207
	v_pk_mul_f32 v[206:207], v[24:25], v[190:191] op_sel_hi:[1,0]
	s_nop 0
	v_cvt_pk_bf16_f32 v206, v206, v207
	v_cvt_pk_bf16_f32 v207, v208, v209
	v_mad_i64_i32 v[208:209], s[2:3], v174, s41, v[148:149]
	v_lshl_add_u64 v[208:209], v[208:209], 0, v[150:151]
	global_store_dwordx4 v[208:209], v[204:207], off
	v_mad_i64_i32 v[148:149], s[2:3], v170, s41, v[148:149]
	s_nop 0
	v_pk_mul_f32 v[204:205], v[20:21], v[190:191] op_sel_hi:[1,0]
	v_pk_mul_f32 v[206:207], v[22:23], v[190:191] op_sel_hi:[1,0]
	v_cvt_pk_bf16_f32 v204, v204, v205
	v_lshl_add_u64 v[148:149], v[148:149], 0, v[150:151]
	v_cvt_pk_bf16_f32 v205, v206, v207
	v_pk_mul_f32 v[206:207], v[16:17], v[190:191] op_sel_hi:[1,0]
	v_pk_mul_f32 v[190:191], v[18:19], v[190:191] op_sel_hi:[1,0]
	v_cvt_pk_bf16_f32 v206, v206, v207
	v_pk_mul_f32 v[150:151], v[6:7], v[188:189] op_sel_hi:[1,0]
	v_cvt_pk_bf16_f32 v207, v190, v191
	global_store_dwordx4 v[208:209], v[204:207], off offset:256
	v_pk_mul_f32 v[208:209], v[10:11], v[188:189] op_sel_hi:[1,0]
	v_mad_i64_i32 v[190:191], s[2:3], v170, s41, 0
	v_pk_mul_f32 v[204:205], v[12:13], v[188:189] op_sel_hi:[1,0]
	v_pk_mul_f32 v[206:207], v[14:15], v[188:189] op_sel_hi:[1,0]
	v_cvt_pk_bf16_f32 v204, v204, v205
	s_nop 0
	v_cvt_pk_bf16_f32 v205, v206, v207
	v_pk_mul_f32 v[206:207], v[8:9], v[188:189] op_sel_hi:[1,0]
	s_nop 0
	v_cvt_pk_bf16_f32 v206, v206, v207
	v_cvt_pk_bf16_f32 v207, v208, v209
	global_store_dwordx4 v[148:149], v[204:207], off
	v_pk_mul_f32 v[148:149], v[4:5], v[188:189] op_sel_hi:[1,0]
	s_nop 0
	v_cvt_pk_bf16_f32 v148, v148, v149
	v_cvt_pk_bf16_f32 v149, v150, v151
	v_pk_mul_f32 v[150:151], v[0:1], v[188:189] op_sel_hi:[1,0]
	v_pk_mul_f32 v[204:205], v[2:3], v[188:189] op_sel_hi:[1,0]
	v_cvt_pk_bf16_f32 v150, v150, v151
	s_nop 0
	v_cvt_pk_bf16_f32 v151, v204, v205
	s_cbranch_execz .LBB0_385
	s_branch .LBB0_386

; __device__ __forceinline__ unsigned cvt_pk_bf16(float lo, float hi) { unsigned r; asm volatile("v_cvt_pk_bf16_f32 %0, %1, %2" : "=v"(r) : "v"(lo), "v"(hi)); return r; }
; template <int NP> __device__ __forceinline__ void load_rs(const float* ssp, int row0, int fq, float (&rs)[2][4]) {
;     ...
;             for (int m = 0; m < 4; ++m) { float s = (p[ai][m][0] + p[ai][m][1]) + (p[ai][m][2] + p[ai][m][3]); s += __shfl_xor(s, 16); s += __shfl_xor(s, 32); rs[ai][m] = s; }
;     }
; #pragma unroll
;     for (int ai = 0; ai < 2; ++ai)
; #pragma unroll
;         for (int m = 0; m < 4; ++m) rs[ai][m] = __builtin_amdgcn_rsqf(rs[ai][m] * (1.0f / D_MODEL) + RMS_EPS);
;     template <bool GATE> __device__ __forceinline__ void body(const f32x4 (&acc)[2][2][4][2], const Unit& u, int wr, int wc, int fr, int fq) const {
;     ...
;                 const int row = row0 + ai * HALF + m * 16; const float r = rs[ai][m], nrl = r * -1.44269504089f;
; #pragma unroll
;                 for (int bj = 0; bj < 2; ++bj) {
;                     unsigned pk[4];
; #pragma unroll
;                     for (int q = 0; q < 4; ++q) {
;                         const f32x4 va = acc[ai][bj][m][q >> 1]; const int e0 = 2 * (q & 1);
;                         const f32x2 v = (f32x2){va[e0], va[e0 + 1]};
;                         f32x2 o;
;                         if (GATE) { const f32x2 t = v * nrl; f32x2 ex; ex.x = __builtin_amdgcn_exp2f(t.x); ex.y = __builtin_amdgcn_exp2f(t.y);
;                             const f32x2 d = ex + 1.0f; o.x = __builtin_amdgcn_rcpf(d.x); o.y = __builtin_amdgcn_rcpf(d.y); }
;                         else o = v * r;
;                         pk[q] = cvt_pk_bf16(o.x, o.y);
;                     }
;                     u32x4 w; w.x = pk[0]; w.y = pk[1]; w.z = pk[2]; w.w = pk[3];
;                     *(u32x4*)(P + (size_t)row * PITCH + col0 + bj * HALF) = w;
.LBB0_385:
	v_mov_b32_e32 v236, v177
	v_mov_b32_e32 v237, v177
	s_nop 1
	v_permlane16_swap_b32_e32 v236, v237
	v_cndmask_b32_e64 v150, v237, v236, s[98:99]
	v_mov_b32_e32 v148, v141
	v_mov_b32_e32 v149, v142
	v_mov_b32_e32 v236, v179
	v_mov_b32_e32 v237, v179
	s_nop 1
	v_permlane16_swap_b32_e32 v236, v237
	v_cndmask_b32_e64 v151, v237, v236, s[98:99]
	v_mov_b32_e32 v236, v181
	v_mov_b32_e32 v237, v181
	s_nop 1
	v_permlane16_swap_b32_e32 v236, v237
	v_cndmask_b32_e64 v183, v237, v236, s[98:99]
	s_waitcnt lgkmcnt(2)
	v_add_f32_e32 v141, v177, v150
	v_mov_b32_e32 v236, v141
	v_mov_b32_e32 v237, v141
	s_nop 1
	v_permlane32_swap_b32_e32 v236, v237
	v_cndmask_b32_e64 v142, v237, v236, s[100:101]
	v_readlane_b32 s2, v235, 44
	s_waitcnt lgkmcnt(2)
	v_add_f32_e32 v150, v179, v151
	v_mov_b32_e32 v236, v150
	v_mov_b32_e32 v237, v150
	s_nop 1
	v_permlane32_swap_b32_e32 v236, v237
	v_cndmask_b32_e64 v177, v237, v236, s[100:101]
	s_waitcnt lgkmcnt(2)
	v_add_f32_e32 v151, v181, v183
	s_waitcnt lgkmcnt(1)
	v_add_f32_e32 v142, v141, v142
	v_mov_b32_e32 v141, v143
	v_pk_add_f32 v[140:141], v[148:149], v[140:141]
	v_mov_b32_e32 v236, v151
	v_mov_b32_e32 v237, v151
	s_nop 1
	v_permlane32_swap_b32_e32 v236, v237
	v_cndmask_b32_e64 v179, v237, v236, s[100:101]
	v_add_f32_e32 v143, v140, v141
	v_mov_b32_e32 v140, v145
	v_mov_b32_e32 v141, v146
	v_mov_b32_e32 v145, v147
	v_pk_add_f32 v[140:141], v[140:141], v[144:145]
	v_mov_b32_e32 v236, v143
	v_mov_b32_e32 v237, v143
	s_nop 1
	v_permlane16_swap_b32_e32 v236, v237
	v_cndmask_b32_e64 v148, v237, v236, s[98:99]
	v_add_f32_e32 v140, v140, v141
	v_mov_b32_e32 v236, v140
	v_mov_b32_e32 v237, v140
	s_nop 1
	v_permlane16_swap_b32_e32 v236, v237
	v_cndmask_b32_e64 v141, v237, v236, s[98:99]
	s_waitcnt lgkmcnt(3)
	v_add_f32_e32 v144, v150, v177
	s_waitcnt lgkmcnt(2)
	v_add_f32_e32 v145, v151, v179
	s_waitcnt lgkmcnt(1)
	v_add_f32_e32 v143, v143, v148
	v_mov_b32_e32 v236, v143
	v_mov_b32_e32 v237, v143
	s_nop 1
	v_permlane32_swap_b32_e32 v236, v237
	v_cndmask_b32_e64 v146, v237, v236, s[100:101]
	s_waitcnt lgkmcnt(1)
	v_add_f32_e32 v147, v140, v141
	v_mov_b32_e32 v140, v133
	v_mov_b32_e32 v141, v134
	v_mov_b32_e32 v133, v135
	v_pk_add_f32 v[132:133], v[140:141], v[132:133]
	v_mov_b32_e32 v236, v147
	v_mov_b32_e32 v237, v147
	s_nop 1
	v_permlane32_swap_b32_e32 v236, v237
	v_cndmask_b32_e64 v148, v237, v236, s[100:101]
	v_add_f32_e32 v134, v132, v133
	v_mov_b32_e32 v132, v137
	v_mov_b32_e32 v133, v138
	v_mov_b32_e32 v137, v139
	v_pk_add_f32 v[132:133], v[132:133], v[136:137]
	v_mov_b32_e32 v236, v134
	v_mov_b32_e32 v237, v134
	s_nop 1
	v_permlane16_swap_b32_e32 v236, v237
	v_cndmask_b32_e64 v135, v237, v236, s[98:99]
	v_add_f32_e32 v136, v132, v133
	v_mov_b32_e32 v132, v129
	v_mov_b32_e32 v133, v130
	v_mov_b32_e32 v129, v131
	v_pk_add_f32 v[128:129], v[132:133], v[128:129]
	v_mov_b32_e32 v236, v136
	v_mov_b32_e32 v237, v136
	s_nop 1
	v_permlane16_swap_b32_e32 v236, v237
	v_cndmask_b32_e64 v137, v237, v236, s[98:99]
	v_add_f32_e32 v128, v128, v129
	v_mov_b32_e32 v236, v128
	v_mov_b32_e32 v237, v128
	s_nop 1
	v_permlane16_swap_b32_e32 v236, v237
	v_cndmask_b32_e64 v129, v237, v236, s[98:99]
	s_waitcnt lgkmcnt(2)
	v_add_f32_e32 v130, v134, v135
	v_mov_b32_e32 v236, v130
	v_mov_b32_e32 v237, v130
	s_nop 1
	v_permlane32_swap_b32_e32 v236, v237
	v_cndmask_b32_e64 v131, v237, v236, s[100:101]
	s_waitcnt lgkmcnt(2)
	v_add_f32_e32 v132, v136, v137
	v_mov_b32_e32 v236, v132
	v_mov_b32_e32 v237, v132
	s_nop 1
	v_permlane32_swap_b32_e32 v236, v237
	v_cndmask_b32_e64 v133, v237, v236, s[100:101]
	s_waitcnt lgkmcnt(2)
	v_add_f32_e32 v128, v128, v129
	v_mov_b32_e32 v236, v128
	v_mov_b32_e32 v237, v128
	s_nop 1
	v_permlane32_swap_b32_e32 v236, v237
	v_cndmask_b32_e64 v129, v237, v236, s[100:101]
	s_waitcnt lgkmcnt(2)
	v_add_f32_e32 v130, v130, v131
	v_add_f32_e32 v134, v143, v146
	s_waitcnt lgkmcnt(1)
	v_add_f32_e32 v131, v132, v133
	v_add_f32_e32 v135, v147, v148
	s_waitcnt lgkmcnt(0)
	v_add_f32_e32 v128, v128, v129
	v_fmamk_f32 v129, v142, 0x3a800000, v202
	v_rsq_f32_e32 v132, v129
	s_nop 0
	v_mov_b32_e32 v240, v132
	v_fmamk_f32 v129, v144, 0x3a800000, v202
	v_rsq_f32_e32 v133, v129
	s_nop 0
	v_mov_b32_e32 v241, v133
	v_fmamk_f32 v129, v145, 0x3a800000, v202
	v_mul_f32_e32 v132, 0xbfb8aa3b, v132
	v_rsq_f32_e32 v136, v129
	s_nop 0
	v_mov_b32_e32 v242, v136
	v_pk_mul_f32 v[124:125], v[124:125], v[132:133] op_sel_hi:[1,0]
	v_pk_mul_f32 v[120:121], v[120:121], v[132:133] op_sel_hi:[1,0]
	v_exp_f32_e32 v124, v124
	v_exp_f32_e32 v125, v125
	v_pk_mul_f32 v[126:127], v[126:127], v[132:133] op_sel_hi:[1,0]
	v_exp_f32_e32 v120, v120
	v_exp_f32_e32 v121, v121
	v_pk_mul_f32 v[122:123], v[122:123], v[132:133] op_sel_hi:[1,0]
	v_exp_f32_e32 v126, v126
	v_exp_f32_e32 v127, v127
	v_exp_f32_e32 v122, v122
	v_exp_f32_e32 v123, v123
	v_fmamk_f32 v129, v134, 0x3a800000, v202
	v_rsq_f32_e32 v137, v129
	s_nop 0
	v_mov_b32_e32 v243, v137
	v_fmamk_f32 v129, v135, 0x3a800000, v202
	v_rsq_f32_e32 v138, v129
	s_nop 0
	v_mov_b32_e32 v244, v138
	v_fmamk_f32 v129, v130, 0x3a800000, v202
	v_pk_add_f32 v[124:125], v[124:125], 1.0 op_sel_hi:[1,0]
	v_pk_add_f32 v[120:121], v[120:121], 1.0 op_sel_hi:[1,0]
	v_pk_mul_f32 v[116:117], v[116:117], v[132:133] op_sel_hi:[1,0]
	v_pk_mul_f32 v[112:113], v[112:113], v[132:133] op_sel_hi:[1,0]
	v_rsq_f32_e32 v130, v129
	s_nop 0
	v_mov_b32_e32 v245, v130
	v_fmamk_f32 v129, v131, 0x3a800000, v202
	v_rcp_f32_e32 v131, v124
	v_rcp_f32_e32 v134, v125
	v_pk_add_f32 v[124:125], v[126:127], 1.0 op_sel_hi:[1,0]
	v_rcp_f32_e32 v127, v120
	v_rcp_f32_e32 v135, v121
	v_pk_add_f32 v[120:121], v[122:123], 1.0 op_sel_hi:[1,0]
	v_exp_f32_e32 v116, v116
; __device__ __forceinline__ unsigned cvt_pk_bf16(float lo, float hi) { unsigned r; asm volatile("v_cvt_pk_bf16_f32 %0, %1, %2" : "=v"(r) : "v"(lo), "v"(hi)); return r; }
;     template <bool GATE> __device__ __forceinline__ void body(const f32x4 (&acc)[2][2][4][2], const Unit& u, int wr, int wc, int fr, int fq) const {
;     ...
;                 const int row = row0 + ai * HALF + m * 16; const float r = rs[ai][m], nrl = r * -1.44269504089f;
; #pragma unroll
;                 for (int bj = 0; bj < 2; ++bj) {
;                     unsigned pk[4];
; #pragma unroll
;                     for (int q = 0; q < 4; ++q) {
;                         const f32x4 va = acc[ai][bj][m][q >> 1]; const int e0 = 2 * (q & 1);
;                         const f32x2 v = (f32x2){va[e0], va[e0 + 1]};
;                         f32x2 o;
;                         if (GATE) { const f32x2 t = v * nrl; f32x2 ex; ex.x = __builtin_amdgcn_exp2f(t.x); ex.y = __builtin_amdgcn_exp2f(t.y);
;                             const f32x2 d = ex + 1.0f; o.x = __builtin_amdgcn_rcpf(d.x); o.y = __builtin_amdgcn_rcpf(d.y); }
;                         else o = v * r;
;                         pk[q] = cvt_pk_bf16(o.x, o.y);
;                     }
;                     u32x4 w; w.x = pk[0]; w.y = pk[1]; w.z = pk[2]; w.w = pk[3];
;                     *(u32x4*)(P + (size_t)row * PITCH + col0 + bj * HALF) = w;
	v_exp_f32_e32 v117, v117
	v_pk_mul_f32 v[118:119], v[118:119], v[132:133] op_sel_hi:[1,0]
	v_exp_f32_e32 v112, v112
	v_exp_f32_e32 v113, v113
	v_pk_mul_f32 v[114:115], v[114:115], v[132:133] op_sel_hi:[1,0]
	v_rcp_f32_e32 v126, v124
	v_rcp_f32_e32 v125, v125
	v_rcp_f32_e32 v120, v120
	v_rcp_f32_e32 v121, v121
	v_readlane_b32 s3, v235, 45
	v_exp_f32_e32 v118, v118
	v_exp_f32_e32 v119, v119
	v_exp_f32_e32 v114, v114
	v_exp_f32_e32 v115, v115
	v_cvt_pk_bf16_f32 v124, v131, v134
	v_cvt_pk_bf16_f32 v125, v126, v125
	v_cvt_pk_bf16_f32 v126, v127, v135
	v_cvt_pk_bf16_f32 v127, v120, v121
	v_mov_b64_e32 v[120:121], s[2:3]
	v_mad_i64_i32 v[134:135], s[2:3], v186, s41, v[120:121]
	v_lshlrev_b64 v[122:123], 1, v[160:161]
	v_lshl_add_u64 v[134:135], v[134:135], 0, v[122:123]
	v_pk_add_f32 v[116:117], v[116:117], 1.0 op_sel_hi:[1,0]
	v_pk_add_f32 v[112:113], v[112:113], 1.0 op_sel_hi:[1,0]
	global_store_dwordx4 v[134:135], v[124:127], off
	v_rsq_f32_e32 v129, v129
	s_nop 0
	v_mov_b32_e32 v246, v129
	v_fmamk_f32 v128, v128, 0x3a800000, v202
	v_rcp_f32_e32 v124, v116
	v_rcp_f32_e32 v125, v117
	v_pk_add_f32 v[116:117], v[118:119], 1.0 op_sel_hi:[1,0]
	v_rcp_f32_e32 v118, v112
	v_rcp_f32_e32 v119, v113
	v_pk_add_f32 v[112:113], v[114:115], 1.0 op_sel_hi:[1,0]
	v_rcp_f32_e32 v116, v116
	v_rcp_f32_e32 v115, v112
	v_cvt_pk_bf16_f32 v112, v124, v125
	v_rcp_f32_e32 v117, v117
	v_rcp_f32_e32 v126, v113
	v_cvt_pk_bf16_f32 v113, v116, v117
	v_cvt_pk_bf16_f32 v114, v118, v119
	v_cvt_pk_bf16_f32 v115, v115, v126
	global_store_dwordx4 v[134:135], v[112:115], off offset:256
	v_rsq_f32_e32 v128, v128
	s_nop 0
	v_mov_b32_e32 v247, v128
	v_mov_b32_e32 v248, s33
rsc_joinb_2:
	v_mad_i64_i32 v[190:191], s[2:3], v170, s41, 0
	v_mul_f32_e32 v112, 0xbfb8aa3b, v133
	v_pk_mul_f32 v[108:109], v[108:109], v[112:113] op_sel_hi:[1,0]
	v_pk_mul_f32 v[110:111], v[110:111], v[112:113] op_sel_hi:[1,0]
	v_exp_f32_e32 v108, v108
	v_exp_f32_e32 v109, v109
	v_exp_f32_e32 v110, v110
	v_exp_f32_e32 v111, v111
	v_pk_add_f32 v[108:109], v[108:109], 1.0 op_sel_hi:[1,0]
	s_nop 0
	v_rcp_f32_e32 v113, v108
	v_rcp_f32_e32 v114, v109
	v_pk_add_f32 v[108:109], v[110:111], 1.0 op_sel_hi:[1,0]
	v_pk_mul_f32 v[104:105], v[104:105], v[112:113] op_sel_hi:[1,0]
	s_nop 0
	v_exp_f32_e32 v104, v104
	v_exp_f32_e32 v105, v105
	v_pk_mul_f32 v[106:107], v[106:107], v[112:113] op_sel_hi:[1,0]
	v_pk_mul_f32 v[100:101], v[100:101], v[112:113] op_sel_hi:[1,0]
	v_exp_f32_e32 v106, v106
	v_exp_f32_e32 v107, v107
	v_pk_mul_f32 v[96:97], v[96:97], v[112:113] op_sel_hi:[1,0]
	v_exp_f32_e32 v100, v100
	v_exp_f32_e32 v101, v101
	v_pk_mul_f32 v[102:103], v[102:103], v[112:113] op_sel_hi:[1,0]
	v_exp_f32_e32 v96, v96
	v_exp_f32_e32 v97, v97
	v_pk_mul_f32 v[98:99], v[98:99], v[112:113] op_sel_hi:[1,0]
	v_pk_add_f32 v[104:105], v[104:105], 1.0 op_sel_hi:[1,0]
	v_exp_f32_e32 v102, v102
	v_exp_f32_e32 v103, v103
	v_exp_f32_e32 v98, v98
	v_exp_f32_e32 v99, v99
	v_rcp_f32_e32 v108, v108
	v_rcp_f32_e32 v109, v109
	v_rcp_f32_e32 v110, v104
	v_rcp_f32_e32 v111, v105
	v_pk_add_f32 v[104:105], v[106:107], 1.0 op_sel_hi:[1,0]
	v_pk_add_f32 v[100:101], v[100:101], 1.0 op_sel_hi:[1,0]
	v_rcp_f32_e32 v107, v104
	v_rcp_f32_e32 v115, v105
	v_cvt_pk_bf16_f32 v104, v113, v114
	v_cvt_pk_bf16_f32 v105, v108, v109
	v_mad_i64_i32 v[108:109], s[2:3], v184, s41, v[120:121]
	v_lshl_add_u64 v[108:109], v[108:109], 0, v[122:123]
	v_pk_add_f32 v[96:97], v[96:97], 1.0 op_sel_hi:[1,0]
	v_cvt_pk_bf16_f32 v106, v110, v111
	v_cvt_pk_bf16_f32 v107, v107, v115
	global_store_dwordx4 v[108:109], v[104:107], off
	s_nop 1
	v_rcp_f32_e32 v104, v100
	v_rcp_f32_e32 v105, v101
	v_pk_add_f32 v[100:101], v[102:103], 1.0 op_sel_hi:[1,0]
	v_rcp_f32_e32 v102, v96
	v_rcp_f32_e32 v103, v97
	v_pk_add_f32 v[96:97], v[98:99], 1.0 op_sel_hi:[1,0]
	v_rcp_f32_e32 v100, v100
	v_rcp_f32_e32 v99, v96
	v_cvt_pk_bf16_f32 v96, v104, v105
	v_rcp_f32_e32 v101, v101
	v_rcp_f32_e32 v106, v97
	v_cvt_pk_bf16_f32 v97, v100, v101
	v_cvt_pk_bf16_f32 v98, v102, v103
	v_cvt_pk_bf16_f32 v99, v99, v106
	global_store_dwordx4 v[108:109], v[96:99], off offset:256
	s_nop 1
	v_mul_f32_e32 v96, 0xbfb8aa3b, v136
	v_pk_mul_f32 v[92:93], v[92:93], v[96:97] op_sel_hi:[1,0]
	v_pk_mul_f32 v[94:95], v[94:95], v[96:97] op_sel_hi:[1,0]
	v_exp_f32_e32 v92, v92
	v_exp_f32_e32 v93, v93
	v_exp_f32_e32 v94, v94
	v_exp_f32_e32 v95, v95
	v_pk_add_f32 v[92:93], v[92:93], 1.0 op_sel_hi:[1,0]
	s_nop 0
	v_rcp_f32_e32 v97, v92
	v_rcp_f32_e32 v98, v93
	v_pk_add_f32 v[92:93], v[94:95], 1.0 op_sel_hi:[1,0]
	v_pk_mul_f32 v[88:89], v[88:89], v[96:97] op_sel_hi:[1,0]
	s_nop 0
	v_exp_f32_e32 v88, v88
	v_exp_f32_e32 v89, v89
	v_pk_mul_f32 v[90:91], v[90:91], v[96:97] op_sel_hi:[1,0]
	v_pk_mul_f32 v[84:85], v[84:85], v[96:97] op_sel_hi:[1,0]
	v_exp_f32_e32 v90, v90
	v_exp_f32_e32 v91, v91
	v_pk_mul_f32 v[80:81], v[80:81], v[96:97] op_sel_hi:[1,0]
	v_exp_f32_e32 v84, v84
	v_exp_f32_e32 v85, v85
	v_pk_mul_f32 v[86:87], v[86:87], v[96:97] op_sel_hi:[1,0]
	v_exp_f32_e32 v80, v80
	v_exp_f32_e32 v81, v81
	v_pk_mul_f32 v[82:83], v[82:83], v[96:97] op_sel_hi:[1,0]
	v_pk_add_f32 v[88:89], v[88:89], 1.0 op_sel_hi:[1,0]
	v_exp_f32_e32 v86, v86
	v_exp_f32_e32 v87, v87
	v_exp_f32_e32 v82, v82
	v_exp_f32_e32 v83, v83
	v_rcp_f32_e32 v92, v92
	v_rcp_f32_e32 v93, v93
	v_rcp_f32_e32 v94, v88
	v_rcp_f32_e32 v95, v89
	v_pk_add_f32 v[88:89], v[90:91], 1.0 op_sel_hi:[1,0]
	v_pk_add_f32 v[84:85], v[84:85], 1.0 op_sel_hi:[1,0]
	v_rcp_f32_e32 v91, v88
	v_rcp_f32_e32 v99, v89
	v_cvt_pk_bf16_f32 v88, v97, v98
	v_cvt_pk_bf16_f32 v89, v92, v93
	v_mad_i64_i32 v[92:93], s[2:3], v182, s41, v[120:121]
	v_lshl_add_u64 v[92:93], v[92:93], 0, v[122:123]
; __device__ __forceinline__ unsigned cvt_pk_bf16(float lo, float hi) { unsigned r; asm volatile("v_cvt_pk_bf16_f32 %0, %1, %2" : "=v"(r) : "v"(lo), "v"(hi)); return r; }
;     template <bool GATE> __device__ __forceinline__ void body(const f32x4 (&acc)[2][2][4][2], const Unit& u, int wr, int wc, int fr, int fq) const {
;     ...
;                 const int row = row0 + ai * HALF + m * 16; const float r = rs[ai][m], nrl = r * -1.44269504089f;
; #pragma unroll
;                 for (int bj = 0; bj < 2; ++bj) {
;                     unsigned pk[4];
; #pragma unroll
;                     for (int q = 0; q < 4; ++q) {
;                         const f32x4 va = acc[ai][bj][m][q >> 1]; const int e0 = 2 * (q & 1);
;                         const f32x2 v = (f32x2){va[e0], va[e0 + 1]};
;                         f32x2 o;
;                         if (GATE) { const f32x2 t = v * nrl; f32x2 ex; ex.x = __builtin_amdgcn_exp2f(t.x); ex.y = __builtin_amdgcn_exp2f(t.y);
;                             const f32x2 d = ex + 1.0f; o.x = __builtin_amdgcn_rcpf(d.x); o.y = __builtin_amdgcn_rcpf(d.y); }
;                         else o = v * r;
;                         pk[q] = cvt_pk_bf16(o.x, o.y);
;                     }
;                     u32x4 w; w.x = pk[0]; w.y = pk[1]; w.z = pk[2]; w.w = pk[3];
;                     *(u32x4*)(P + (size_t)row * PITCH + col0 + bj * HALF) = w;
	v_pk_add_f32 v[80:81], v[80:81], 1.0 op_sel_hi:[1,0]
	v_cvt_pk_bf16_f32 v90, v94, v95
	v_cvt_pk_bf16_f32 v91, v91, v99
	global_store_dwordx4 v[92:93], v[88:91], off
	s_nop 1
	v_rcp_f32_e32 v88, v84
	v_rcp_f32_e32 v89, v85
	v_pk_add_f32 v[84:85], v[86:87], 1.0 op_sel_hi:[1,0]
	v_rcp_f32_e32 v86, v80
	v_rcp_f32_e32 v87, v81
	v_pk_add_f32 v[80:81], v[82:83], 1.0 op_sel_hi:[1,0]
	v_rcp_f32_e32 v84, v84
	v_rcp_f32_e32 v83, v80
	v_cvt_pk_bf16_f32 v80, v88, v89
	v_rcp_f32_e32 v85, v85
	v_rcp_f32_e32 v90, v81
	v_cvt_pk_bf16_f32 v81, v84, v85
	v_cvt_pk_bf16_f32 v82, v86, v87
	v_cvt_pk_bf16_f32 v83, v83, v90
	global_store_dwordx4 v[92:93], v[80:83], off offset:256
	s_nop 1
	v_mul_f32_e32 v80, 0xbfb8aa3b, v137
	v_pk_mul_f32 v[76:77], v[76:77], v[80:81] op_sel_hi:[1,0]
	v_pk_mul_f32 v[78:79], v[78:79], v[80:81] op_sel_hi:[1,0]
	v_exp_f32_e32 v76, v76
	v_exp_f32_e32 v77, v77
	v_exp_f32_e32 v78, v78
	v_exp_f32_e32 v79, v79
	v_pk_add_f32 v[76:77], v[76:77], 1.0 op_sel_hi:[1,0]
	s_nop 0
	v_rcp_f32_e32 v81, v76
	v_rcp_f32_e32 v82, v77
	v_pk_add_f32 v[76:77], v[78:79], 1.0 op_sel_hi:[1,0]
	v_pk_mul_f32 v[72:73], v[72:73], v[80:81] op_sel_hi:[1,0]
	s_nop 0
	v_exp_f32_e32 v72, v72
	v_exp_f32_e32 v73, v73
	v_pk_mul_f32 v[74:75], v[74:75], v[80:81] op_sel_hi:[1,0]
	v_pk_mul_f32 v[68:69], v[68:69], v[80:81] op_sel_hi:[1,0]
	v_exp_f32_e32 v74, v74
	v_exp_f32_e32 v75, v75
	v_pk_mul_f32 v[64:65], v[64:65], v[80:81] op_sel_hi:[1,0]
	v_exp_f32_e32 v68, v68
	v_exp_f32_e32 v69, v69
	v_pk_mul_f32 v[70:71], v[70:71], v[80:81] op_sel_hi:[1,0]
	v_exp_f32_e32 v64, v64
	v_exp_f32_e32 v65, v65
	v_pk_mul_f32 v[66:67], v[66:67], v[80:81] op_sel_hi:[1,0]
	v_pk_add_f32 v[72:73], v[72:73], 1.0 op_sel_hi:[1,0]
	v_exp_f32_e32 v70, v70
	v_exp_f32_e32 v71, v71
	v_exp_f32_e32 v66, v66
	v_exp_f32_e32 v67, v67
	v_rcp_f32_e32 v76, v76
	v_rcp_f32_e32 v77, v77
	v_rcp_f32_e32 v78, v72
	v_rcp_f32_e32 v79, v73
	v_pk_add_f32 v[72:73], v[74:75], 1.0 op_sel_hi:[1,0]
	v_pk_add_f32 v[68:69], v[68:69], 1.0 op_sel_hi:[1,0]
	v_rcp_f32_e32 v75, v72
	v_rcp_f32_e32 v83, v73
	v_cvt_pk_bf16_f32 v72, v81, v82
	v_cvt_pk_bf16_f32 v73, v76, v77
	v_mad_i64_i32 v[76:77], s[2:3], v180, s41, v[120:121]
	v_lshl_add_u64 v[76:77], v[76:77], 0, v[122:123]
	v_pk_add_f32 v[64:65], v[64:65], 1.0 op_sel_hi:[1,0]
	v_cvt_pk_bf16_f32 v74, v78, v79
	v_cvt_pk_bf16_f32 v75, v75, v83
	global_store_dwordx4 v[76:77], v[72:75], off
	s_nop 1
	v_rcp_f32_e32 v72, v68
	v_rcp_f32_e32 v73, v69
	v_pk_add_f32 v[68:69], v[70:71], 1.0 op_sel_hi:[1,0]
	v_rcp_f32_e32 v70, v64
	v_rcp_f32_e32 v71, v65
	v_pk_add_f32 v[64:65], v[66:67], 1.0 op_sel_hi:[1,0]
	v_rcp_f32_e32 v68, v68
	v_rcp_f32_e32 v67, v64
	v_cvt_pk_bf16_f32 v64, v72, v73
	v_rcp_f32_e32 v69, v69
	v_rcp_f32_e32 v74, v65
	v_cvt_pk_bf16_f32 v65, v68, v69
	v_cvt_pk_bf16_f32 v66, v70, v71
	v_cvt_pk_bf16_f32 v67, v67, v74
	global_store_dwordx4 v[76:77], v[64:67], off offset:256
	s_nop 1
	v_mul_f32_e32 v64, 0xbfb8aa3b, v138
	v_pk_mul_f32 v[60:61], v[60:61], v[64:65] op_sel_hi:[1,0]
	v_pk_mul_f32 v[62:63], v[62:63], v[64:65] op_sel_hi:[1,0]
	v_exp_f32_e32 v60, v60
	v_exp_f32_e32 v61, v61
	v_exp_f32_e32 v62, v62
	v_exp_f32_e32 v63, v63
	v_pk_add_f32 v[60:61], v[60:61], 1.0 op_sel_hi:[1,0]
	s_nop 0
	v_rcp_f32_e32 v65, v60
	v_rcp_f32_e32 v66, v61
	v_pk_add_f32 v[60:61], v[62:63], 1.0 op_sel_hi:[1,0]
	v_pk_mul_f32 v[56:57], v[56:57], v[64:65] op_sel_hi:[1,0]
	s_nop 0
	v_exp_f32_e32 v56, v56
	v_exp_f32_e32 v57, v57
	v_pk_mul_f32 v[58:59], v[58:59], v[64:65] op_sel_hi:[1,0]
	v_pk_mul_f32 v[52:53], v[52:53], v[64:65] op_sel_hi:[1,0]
	v_exp_f32_e32 v58, v58
	v_exp_f32_e32 v59, v59
	v_pk_mul_f32 v[48:49], v[48:49], v[64:65] op_sel_hi:[1,0]
	v_exp_f32_e32 v52, v52
	v_exp_f32_e32 v53, v53
	v_pk_mul_f32 v[54:55], v[54:55], v[64:65] op_sel_hi:[1,0]
	v_exp_f32_e32 v48, v48
	v_exp_f32_e32 v49, v49
	v_pk_mul_f32 v[50:51], v[50:51], v[64:65] op_sel_hi:[1,0]
	v_pk_add_f32 v[56:57], v[56:57], 1.0 op_sel_hi:[1,0]
	v_exp_f32_e32 v54, v54
	v_exp_f32_e32 v55, v55
	v_exp_f32_e32 v50, v50
	v_exp_f32_e32 v51, v51
	v_rcp_f32_e32 v60, v60
	v_rcp_f32_e32 v61, v61
	v_rcp_f32_e32 v62, v56
	v_rcp_f32_e32 v63, v57
	v_pk_add_f32 v[56:57], v[58:59], 1.0 op_sel_hi:[1,0]
	v_pk_add_f32 v[52:53], v[52:53], 1.0 op_sel_hi:[1,0]
	v_rcp_f32_e32 v59, v56
	v_rcp_f32_e32 v67, v57
	v_cvt_pk_bf16_f32 v56, v65, v66
	v_cvt_pk_bf16_f32 v57, v60, v61
	v_mad_i64_i32 v[60:61], s[2:3], v178, s41, v[120:121]
	v_lshl_add_u64 v[60:61], v[60:61], 0, v[122:123]
	v_pk_add_f32 v[48:49], v[48:49], 1.0 op_sel_hi:[1,0]
	v_cvt_pk_bf16_f32 v58, v62, v63
	v_cvt_pk_bf16_f32 v59, v59, v67
	global_store_dwordx4 v[60:61], v[56:59], off
	s_nop 1
	v_rcp_f32_e32 v56, v52
	v_rcp_f32_e32 v57, v53
	v_pk_add_f32 v[52:53], v[54:55], 1.0 op_sel_hi:[1,0]
	v_rcp_f32_e32 v54, v48
	v_rcp_f32_e32 v55, v49
	v_pk_add_f32 v[48:49], v[50:51], 1.0 op_sel_hi:[1,0]
	v_rcp_f32_e32 v52, v52
	v_rcp_f32_e32 v51, v48
	v_cvt_pk_bf16_f32 v48, v56, v57
	v_rcp_f32_e32 v53, v53
	v_rcp_f32_e32 v58, v49
	v_cvt_pk_bf16_f32 v49, v52, v53
	v_cvt_pk_bf16_f32 v50, v54, v55
	v_cvt_pk_bf16_f32 v51, v51, v58
	global_store_dwordx4 v[60:61], v[48:51], off offset:256
	s_nop 1
	v_mul_f32_e32 v48, 0xbfb8aa3b, v130
	v_pk_mul_f32 v[44:45], v[44:45], v[48:49] op_sel_hi:[1,0]
	v_pk_mul_f32 v[46:47], v[46:47], v[48:49] op_sel_hi:[1,0]
	v_exp_f32_e32 v44, v44
	v_exp_f32_e32 v45, v45
	v_exp_f32_e32 v46, v46
	v_exp_f32_e32 v47, v47
	v_pk_add_f32 v[44:45], v[44:45], 1.0 op_sel_hi:[1,0]
	s_nop 0
	v_rcp_f32_e32 v49, v44
	v_rcp_f32_e32 v50, v45
	v_pk_add_f32 v[44:45], v[46:47], 1.0 op_sel_hi:[1,0]
	v_pk_mul_f32 v[40:41], v[40:41], v[48:49] op_sel_hi:[1,0]
	s_nop 0
	v_exp_f32_e32 v40, v40
	v_exp_f32_e32 v41, v41
; __device__ __forceinline__ unsigned cvt_pk_bf16(float lo, float hi) { unsigned r; asm volatile("v_cvt_pk_bf16_f32 %0, %1, %2" : "=v"(r) : "v"(lo), "v"(hi)); return r; }
;     template <bool GATE> __device__ __forceinline__ void body(const f32x4 (&acc)[2][2][4][2], const Unit& u, int wr, int wc, int fr, int fq) const {
;     ...
;                 const int row = row0 + ai * HALF + m * 16; const float r = rs[ai][m], nrl = r * -1.44269504089f;
; #pragma unroll
;                 for (int bj = 0; bj < 2; ++bj) {
;                     unsigned pk[4];
; #pragma unroll
;                     for (int q = 0; q < 4; ++q) {
;                         const f32x4 va = acc[ai][bj][m][q >> 1]; const int e0 = 2 * (q & 1);
;                         const f32x2 v = (f32x2){va[e0], va[e0 + 1]};
;                         f32x2 o;
;                         if (GATE) { const f32x2 t = v * nrl; f32x2 ex; ex.x = __builtin_amdgcn_exp2f(t.x); ex.y = __builtin_amdgcn_exp2f(t.y);
;                             const f32x2 d = ex + 1.0f; o.x = __builtin_amdgcn_rcpf(d.x); o.y = __builtin_amdgcn_rcpf(d.y); }
;                         else o = v * r;
;                         pk[q] = cvt_pk_bf16(o.x, o.y);
;                     }
;                     u32x4 w; w.x = pk[0]; w.y = pk[1]; w.z = pk[2]; w.w = pk[3];
;                     *(u32x4*)(P + (size_t)row * PITCH + col0 + bj * HALF) = w;
	v_pk_mul_f32 v[42:43], v[42:43], v[48:49] op_sel_hi:[1,0]
	v_pk_mul_f32 v[36:37], v[36:37], v[48:49] op_sel_hi:[1,0]
	v_exp_f32_e32 v42, v42
	v_exp_f32_e32 v43, v43
	v_pk_mul_f32 v[32:33], v[32:33], v[48:49] op_sel_hi:[1,0]
	v_exp_f32_e32 v36, v36
	v_exp_f32_e32 v37, v37
	v_pk_mul_f32 v[38:39], v[38:39], v[48:49] op_sel_hi:[1,0]
	v_exp_f32_e32 v32, v32
	v_exp_f32_e32 v33, v33
	v_pk_mul_f32 v[34:35], v[34:35], v[48:49] op_sel_hi:[1,0]
	v_pk_add_f32 v[40:41], v[40:41], 1.0 op_sel_hi:[1,0]
	v_exp_f32_e32 v38, v38
	v_exp_f32_e32 v39, v39
	v_exp_f32_e32 v34, v34
	v_exp_f32_e32 v35, v35
	v_rcp_f32_e32 v44, v44
	v_rcp_f32_e32 v45, v45
	v_rcp_f32_e32 v46, v40
	v_rcp_f32_e32 v47, v41
	v_pk_add_f32 v[40:41], v[42:43], 1.0 op_sel_hi:[1,0]
	v_pk_add_f32 v[36:37], v[36:37], 1.0 op_sel_hi:[1,0]
	v_rcp_f32_e32 v43, v40
	v_rcp_f32_e32 v51, v41
	v_cvt_pk_bf16_f32 v40, v49, v50
	v_cvt_pk_bf16_f32 v41, v44, v45
	v_mad_i64_i32 v[44:45], s[2:3], v176, s41, v[120:121]
	v_lshl_add_u64 v[44:45], v[44:45], 0, v[122:123]
	v_pk_add_f32 v[32:33], v[32:33], 1.0 op_sel_hi:[1,0]
	v_cvt_pk_bf16_f32 v42, v46, v47
	v_cvt_pk_bf16_f32 v43, v43, v51
	global_store_dwordx4 v[44:45], v[40:43], off
	s_nop 1
	v_rcp_f32_e32 v40, v36
	v_rcp_f32_e32 v41, v37
	v_pk_add_f32 v[36:37], v[38:39], 1.0 op_sel_hi:[1,0]
	v_rcp_f32_e32 v38, v32
	v_rcp_f32_e32 v39, v33
	v_pk_add_f32 v[32:33], v[34:35], 1.0 op_sel_hi:[1,0]
	v_rcp_f32_e32 v36, v36
	v_rcp_f32_e32 v35, v32
	v_cvt_pk_bf16_f32 v32, v40, v41
	v_rcp_f32_e32 v37, v37
	v_rcp_f32_e32 v42, v33
	v_cvt_pk_bf16_f32 v33, v36, v37
	v_cvt_pk_bf16_f32 v34, v38, v39
	v_cvt_pk_bf16_f32 v35, v35, v42
	global_store_dwordx4 v[44:45], v[32:35], off offset:256
	s_nop 1
	v_mul_f32_e32 v32, 0xbfb8aa3b, v129
	v_pk_mul_f32 v[28:29], v[28:29], v[32:33] op_sel_hi:[1,0]
	v_pk_mul_f32 v[30:31], v[30:31], v[32:33] op_sel_hi:[1,0]
	v_exp_f32_e32 v28, v28
	v_exp_f32_e32 v29, v29
	v_exp_f32_e32 v30, v30
	v_exp_f32_e32 v31, v31
	v_pk_add_f32 v[28:29], v[28:29], 1.0 op_sel_hi:[1,0]
	s_nop 0
	v_rcp_f32_e32 v33, v28
	v_rcp_f32_e32 v34, v29
	v_pk_add_f32 v[28:29], v[30:31], 1.0 op_sel_hi:[1,0]
	v_pk_mul_f32 v[24:25], v[24:25], v[32:33] op_sel_hi:[1,0]
	s_nop 0
	v_exp_f32_e32 v24, v24
	v_exp_f32_e32 v25, v25
	v_pk_mul_f32 v[26:27], v[26:27], v[32:33] op_sel_hi:[1,0]
	v_pk_mul_f32 v[20:21], v[20:21], v[32:33] op_sel_hi:[1,0]
	v_exp_f32_e32 v26, v26
	v_exp_f32_e32 v27, v27
	v_pk_mul_f32 v[16:17], v[16:17], v[32:33] op_sel_hi:[1,0]
	v_exp_f32_e32 v20, v20
	v_exp_f32_e32 v21, v21
	v_pk_mul_f32 v[22:23], v[22:23], v[32:33] op_sel_hi:[1,0]
	v_exp_f32_e32 v16, v16
	v_exp_f32_e32 v17, v17
	v_pk_mul_f32 v[18:19], v[18:19], v[32:33] op_sel_hi:[1,0]
	v_pk_add_f32 v[24:25], v[24:25], 1.0 op_sel_hi:[1,0]
	v_exp_f32_e32 v22, v22
	v_exp_f32_e32 v23, v23
	v_exp_f32_e32 v18, v18
	v_exp_f32_e32 v19, v19
	v_rcp_f32_e32 v28, v28
	v_rcp_f32_e32 v29, v29
	v_rcp_f32_e32 v30, v24
	v_rcp_f32_e32 v31, v25
	v_pk_add_f32 v[24:25], v[26:27], 1.0 op_sel_hi:[1,0]
	v_pk_add_f32 v[20:21], v[20:21], 1.0 op_sel_hi:[1,0]
	v_rcp_f32_e32 v27, v24
	v_rcp_f32_e32 v35, v25
	v_cvt_pk_bf16_f32 v24, v33, v34
	v_cvt_pk_bf16_f32 v25, v28, v29
	v_mad_i64_i32 v[28:29], s[2:3], v174, s41, v[120:121]
	v_lshl_add_u64 v[28:29], v[28:29], 0, v[122:123]
	v_pk_add_f32 v[16:17], v[16:17], 1.0 op_sel_hi:[1,0]
	v_cvt_pk_bf16_f32 v26, v30, v31
	v_cvt_pk_bf16_f32 v27, v27, v35
	global_store_dwordx4 v[28:29], v[24:27], off
	s_nop 1
	v_rcp_f32_e32 v24, v20
	v_rcp_f32_e32 v25, v21
	v_pk_add_f32 v[20:21], v[22:23], 1.0 op_sel_hi:[1,0]
	v_rcp_f32_e32 v22, v16
	v_rcp_f32_e32 v23, v17
	v_pk_add_f32 v[16:17], v[18:19], 1.0 op_sel_hi:[1,0]
	v_rcp_f32_e32 v20, v20
	v_rcp_f32_e32 v19, v16
	v_cvt_pk_bf16_f32 v16, v24, v25
	v_rcp_f32_e32 v21, v21
	v_rcp_f32_e32 v26, v17
	v_cvt_pk_bf16_f32 v17, v20, v21
	v_cvt_pk_bf16_f32 v18, v22, v23
	v_cvt_pk_bf16_f32 v19, v19, v26
	global_store_dwordx4 v[28:29], v[16:19], off offset:256
	s_nop 1
	v_mul_f32_e32 v16, 0xbfb8aa3b, v128
	v_pk_mul_f32 v[12:13], v[12:13], v[16:17] op_sel_hi:[1,0]
	v_pk_mul_f32 v[14:15], v[14:15], v[16:17] op_sel_hi:[1,0]
	v_exp_f32_e32 v12, v12
	v_exp_f32_e32 v13, v13
	v_exp_f32_e32 v14, v14
	v_exp_f32_e32 v15, v15
	v_pk_add_f32 v[12:13], v[12:13], 1.0 op_sel_hi:[1,0]
	s_nop 0
	v_rcp_f32_e32 v17, v12
	v_rcp_f32_e32 v18, v13
	v_pk_add_f32 v[12:13], v[14:15], 1.0 op_sel_hi:[1,0]
	v_pk_mul_f32 v[8:9], v[8:9], v[16:17] op_sel_hi:[1,0]
	s_nop 0
	v_exp_f32_e32 v8, v8
	v_exp_f32_e32 v9, v9
	v_pk_mul_f32 v[10:11], v[10:11], v[16:17] op_sel_hi:[1,0]
	v_pk_mul_f32 v[4:5], v[4:5], v[16:17] op_sel_hi:[1,0]
	v_exp_f32_e32 v10, v10
	v_exp_f32_e32 v11, v11
	v_pk_mul_f32 v[0:1], v[0:1], v[16:17] op_sel_hi:[1,0]
	v_exp_f32_e32 v4, v4
	v_exp_f32_e32 v5, v5
	v_pk_mul_f32 v[6:7], v[6:7], v[16:17] op_sel_hi:[1,0]
	v_exp_f32_e32 v0, v0
	v_exp_f32_e32 v1, v1
	v_pk_mul_f32 v[2:3], v[2:3], v[16:17] op_sel_hi:[1,0]
	v_pk_add_f32 v[8:9], v[8:9], 1.0 op_sel_hi:[1,0]
	v_exp_f32_e32 v6, v6
	v_exp_f32_e32 v7, v7
	v_exp_f32_e32 v2, v2
	v_exp_f32_e32 v3, v3
	v_rcp_f32_e32 v12, v12
	v_rcp_f32_e32 v13, v13
	v_rcp_f32_e32 v14, v8
	v_rcp_f32_e32 v15, v9
	v_pk_add_f32 v[8:9], v[10:11], 1.0 op_sel_hi:[1,0]
	v_pk_add_f32 v[4:5], v[4:5], 1.0 op_sel_hi:[1,0]
	v_rcp_f32_e32 v11, v8
	v_rcp_f32_e32 v19, v9
	v_cvt_pk_bf16_f32 v8, v17, v18
	v_cvt_pk_bf16_f32 v9, v12, v13
	v_mad_i64_i32 v[12:13], s[2:3], v170, s41, v[120:121]
	v_lshl_add_u64 v[12:13], v[12:13], 0, v[122:123]
	v_pk_add_f32 v[0:1], v[0:1], 1.0 op_sel_hi:[1,0]
	v_cvt_pk_bf16_f32 v10, v14, v15
	v_cvt_pk_bf16_f32 v11, v11, v19
	global_store_dwordx4 v[12:13], v[8:11], off
	s_nop 1
	v_rcp_f32_e32 v8, v4
	v_rcp_f32_e32 v9, v5
	v_pk_add_f32 v[4:5], v[6:7], 1.0 op_sel_hi:[1,0]
	v_rcp_f32_e32 v6, v0
	v_rcp_f32_e32 v7, v1
	v_pk_add_f32 v[0:1], v[2:3], 1.0 op_sel_hi:[1,0]
	v_rcp_f32_e32 v4, v4
	v_rcp_f32_e32 v5, v5
	v_rcp_f32_e32 v0, v0
	v_rcp_f32_e32 v1, v1
	v_cvt_pk_bf16_f32 v148, v8, v9
	v_cvt_pk_bf16_f32 v149, v4, v5
	v_cvt_pk_bf16_f32 v150, v6, v7
	v_cvt_pk_bf16_f32 v151, v0, v1
	s_branch .LBB0_386
; __device__ __forceinline__ unsigned cvt_pk_bf16(float lo, float hi) { unsigned r; asm volatile("v_cvt_pk_bf16_f32 %0, %1, %2" : "=v"(r) : "v"(lo), "v"(hi)); return r; }
;     template <bool GATE> __device__ __forceinline__ void body(const f32x4 (&acc)[2][2][4][2], const Unit& u, int wr, int wc, int fr, int fq) const {
;         const int row0 = u.pm * BM + wr * 64 + fr, col0 = u.pn * BM + wc * 32 + 8 * fq;
;         float rs[2][4]; load_rs<16>(ssp, row0, fq, rs);
; #pragma unroll
;         for (int ai = 0; ai < 2; ++ai)
; #pragma unroll
;             for (int m = 0; m < 4; ++m) {
;                 const int row = row0 + ai * HALF + m * 16; const float r = rs[ai][m], nrl = r * -1.44269504089f;
; #pragma unroll
;                 for (int bj = 0; bj < 2; ++bj) {
;                     unsigned pk[4];
; #pragma unroll
;                     for (int q = 0; q < 4; ++q) {
;                         const f32x4 va = acc[ai][bj][m][q >> 1]; const int e0 = 2 * (q & 1);
;                         const f32x2 v = (f32x2){va[e0], va[e0 + 1]};
;                         f32x2 o;
;                         if (GATE) { const f32x2 t = v * nrl; f32x2 ex; ex.x = __builtin_amdgcn_exp2f(t.x); ex.y = __builtin_amdgcn_exp2f(t.y);
;                             const f32x2 d = ex + 1.0f; o.x = __builtin_amdgcn_rcpf(d.x); o.y = __builtin_amdgcn_rcpf(d.y); }
;                         else o = v * r;
;                         pk[q] = cvt_pk_bf16(o.x, o.y);
;                     }
;                     u32x4 w; w.x = pk[0]; w.y = pk[1]; w.z = pk[2]; w.w = pk[3];
;                     *(u32x4*)(P + (size_t)row * PITCH + col0 + bj * HALF) = w;
rsc_hit_2:
	v_lshl_add_u32 v186, s33, 8, v193
	v_or_b32_e32 v184, 16, v186
	s_nop 3
	v_or_b32_e32 v182, 32, v186
	v_or_b32_e32 v180, 48, v186
	s_nop 4
	v_add_u32_e32 v178, 0x80, v186
	v_add_u32_e32 v176, 0x90, v186
	v_add_u32_e32 v174, 0xa0, v186
	v_add_u32_e32 v170, 0xb0, v186
	v_and_b32_e32 v172, 64, v201
	v_xor_b32_e32 v171, 16, v201
	v_add_u32_e32 v172, 64, v172
	v_xor_b32_e32 v173, 32, v201
	v_cmp_lt_i32_e32 vcc, v171, v172
	s_cmp_lt_i32 s43, 9
	v_lshl_or_b32 v160, s43, 8, v197
	v_cndmask_b32_e32 v171, v201, v171, vcc
	v_cmp_lt_i32_e32 vcc, v173, v172
	v_lshlrev_b32_e32 v175, 2, v171
	s_waitcnt vmcnt(0)
	s_nop 1
	v_cndmask_b32_e32 v172, v201, v173, vcc
	s_nop 2
	v_lshlrev_b32_e32 v171, 2, v172
	s_cbranch_scc0 rsc_hitb_2
	v_mov_b32_e32 v208, v240
	v_mov_b32_e32 v210, v241
	v_mov_b32_e32 v212, v242
	v_mov_b32_e32 v214, v243
	v_mov_b32_e32 v194, v244
	v_mov_b32_e32 v192, v245
	v_mov_b32_e32 v190, v246
	v_mov_b32_e32 v188, v247
	s_waitcnt lgkmcnt(0)
	s_branch rsc_joina_2
rsc_hitb_2:
	v_mov_b64_e32 v[172:173], v[160:161]
	v_readlane_b32 s2, v235, 44
	v_mov_b32_e32 v132, v240
	s_nop 0
	v_mov_b32_e32 v133, v241
	s_nop 0
	v_mul_f32_e32 v132, 0xbfb8aa3b, v132
	v_mov_b32_e32 v136, v242
	v_pk_mul_f32 v[124:125], v[124:125], v[132:133] op_sel_hi:[1,0]
	v_pk_mul_f32 v[120:121], v[120:121], v[132:133] op_sel_hi:[1,0]
	v_exp_f32_e32 v124, v124
	v_exp_f32_e32 v125, v125
	v_pk_mul_f32 v[126:127], v[126:127], v[132:133] op_sel_hi:[1,0]
	v_exp_f32_e32 v120, v120
	v_exp_f32_e32 v121, v121
	v_pk_mul_f32 v[122:123], v[122:123], v[132:133] op_sel_hi:[1,0]
	v_exp_f32_e32 v126, v126
	v_exp_f32_e32 v127, v127
	v_exp_f32_e32 v122, v122
	v_exp_f32_e32 v123, v123
	v_mov_b32_e32 v137, v243
	v_mov_b32_e32 v138, v244
	v_pk_add_f32 v[124:125], v[124:125], 1.0 op_sel_hi:[1,0]
	v_pk_add_f32 v[120:121], v[120:121], 1.0 op_sel_hi:[1,0]
	v_pk_mul_f32 v[116:117], v[116:117], v[132:133] op_sel_hi:[1,0]
	v_pk_mul_f32 v[112:113], v[112:113], v[132:133] op_sel_hi:[1,0]
	v_mov_b32_e32 v130, v245
	s_nop 0
	v_rcp_f32_e32 v131, v124
	v_rcp_f32_e32 v134, v125
	v_pk_add_f32 v[124:125], v[126:127], 1.0 op_sel_hi:[1,0]
	v_rcp_f32_e32 v127, v120
	v_rcp_f32_e32 v135, v121
	v_pk_add_f32 v[120:121], v[122:123], 1.0 op_sel_hi:[1,0]
	v_exp_f32_e32 v116, v116
	v_exp_f32_e32 v117, v117
	v_pk_mul_f32 v[118:119], v[118:119], v[132:133] op_sel_hi:[1,0]
	v_exp_f32_e32 v112, v112
	v_exp_f32_e32 v113, v113
	v_pk_mul_f32 v[114:115], v[114:115], v[132:133] op_sel_hi:[1,0]
	v_rcp_f32_e32 v126, v124
	v_rcp_f32_e32 v125, v125
	v_rcp_f32_e32 v120, v120
	v_rcp_f32_e32 v121, v121
	v_readlane_b32 s3, v235, 45
	v_exp_f32_e32 v118, v118
	v_exp_f32_e32 v119, v119
	v_exp_f32_e32 v114, v114
	v_exp_f32_e32 v115, v115
	v_cvt_pk_bf16_f32 v124, v131, v134
	v_cvt_pk_bf16_f32 v125, v126, v125
	v_cvt_pk_bf16_f32 v126, v127, v135
	v_cvt_pk_bf16_f32 v127, v120, v121
	v_mov_b64_e32 v[120:121], s[2:3]
	v_mad_i64_i32 v[134:135], s[2:3], v186, s41, v[120:121]
	v_lshlrev_b64 v[122:123], 1, v[160:161]
	v_lshl_add_u64 v[134:135], v[134:135], 0, v[122:123]
	v_pk_add_f32 v[116:117], v[116:117], 1.0 op_sel_hi:[1,0]
	v_pk_add_f32 v[112:113], v[112:113], 1.0 op_sel_hi:[1,0]
	global_store_dwordx4 v[134:135], v[124:127], off
	v_mov_b32_e32 v129, v246
	s_nop 0
	v_rcp_f32_e32 v124, v116
	v_rcp_f32_e32 v125, v117
	v_pk_add_f32 v[116:117], v[118:119], 1.0 op_sel_hi:[1,0]
	v_rcp_f32_e32 v118, v112
	v_rcp_f32_e32 v119, v113
	v_pk_add_f32 v[112:113], v[114:115], 1.0 op_sel_hi:[1,0]
	v_rcp_f32_e32 v116, v116
	v_rcp_f32_e32 v115, v112
	v_cvt_pk_bf16_f32 v112, v124, v125
	v_rcp_f32_e32 v117, v117
	v_rcp_f32_e32 v126, v113
	v_cvt_pk_bf16_f32 v113, v116, v117
	v_cvt_pk_bf16_f32 v114, v118, v119
	v_cvt_pk_bf16_f32 v115, v115, v126
	global_store_dwordx4 v[134:135], v[112:115], off offset:256
	v_mov_b32_e32 v128, v247
	s_waitcnt lgkmcnt(0)
	s_branch rsc_joinb_2

; template <int NP> __device__ __forceinline__ void load_rs(const float* ssp, int row0, int fq, float (&rs)[2][4]) {
;     ...
;         f32x4 p[2][4];
; #pragma unroll
;         for (int ai = 0; ai < 2; ++ai)
; #pragma unroll
;             for (int m = 0; m < 4; ++m) p[ai][m] = *(const f32x4*)(ssp + (size_t)(row0 + ai * HALF + m * 16) * 16 + 4 * fq);
; #pragma unroll
;         for (int ai = 0; ai < 2; ++ai)
; #pragma unroll
;             for (int m = 0; m < 4; ++m) { float s = (p[ai][m][0] + p[ai][m][1]) + (p[ai][m][2] + p[ai][m][3]); s += __shfl_xor(s, 16); s += __shfl_xor(s, 32); rs[ai][m] = s; }
;     }
; #pragma unroll
;     for (int ai = 0; ai < 2; ++ai)
; #pragma unroll
;         for (int m = 0; m < 4; ++m) rs[ai][m] = __builtin_amdgcn_rsqf(rs[ai][m] * (1.0f / D_MODEL) + RMS_EPS);
;     __device__ __forceinline__ void operator()(const f32x4 (&acc)[2][2][4][2], const Unit& u, int wr, int wc, int fr, int fq) const {
;     ...
;                 const int row = row0 + ai * HALF + m * 16; const float r = rs[ai][m];
;                 const float nrl = r * -1.44269504089f, r2 = r * r;
;                 unsigned pk[4];
; #pragma unroll
;                 for (int q = 0; q < 4; ++q) {
;                     const f32x4 ga = acc[ai][0][m][q >> 1], ua = acc[ai][1][m][q >> 1]; const int e0 = 2 * (q & 1);
;                     const f32x2 g = (f32x2){ga[e0], ga[e0 + 1]}, up = (f32x2){ua[e0], ua[e0 + 1]};
;                     const f32x2 t = g * nrl; f32x2 ex; ex.x = __builtin_amdgcn_exp2f(t.x); ex.y = __builtin_amdgcn_exp2f(t.y);
;                     const f32x2 d = ex + 1.0f; f32x2 rc; rc.x = __builtin_amdgcn_rcpf(d.x); rc.y = __builtin_amdgcn_rcpf(d.y);
;                     const f32x2 o = (g * up) * (rc * r2);
.LBB0_932:
	v_cmp_eq_u32_e32 vcc, s41, v248
	s_cbranch_vccnz rsc_hit_1
	s_lshl_b32 s2, s41, 8
	s_add_i32 s2, s2, s29
	v_or_b32_e32 v146, s2, v150
	v_ashrrev_i32_e32 v147, 31, v146
	v_or_b32_e32 v160, 16, v146
	v_lshlrev_b64 v[148:149], 6, v[146:147]
	v_ashrrev_i32_e32 v161, 31, v160
	v_or_b32_e32 v168, 32, v146
	v_or_b32_e32 v170, 48, v146
	v_add_u32_e32 v146, 0x80, v146
	v_lshlrev_b64 v[160:161], 6, v[160:161]
	v_ashrrev_i32_e32 v169, 31, v168
	v_ashrrev_i32_e32 v171, 31, v170
	v_ashrrev_i32_e32 v147, 31, v146
	v_lshl_add_u64 v[148:149], v[138:139], 0, v[148:149]
	v_lshl_add_u64 v[164:165], v[138:139], 0, v[160:161]
	v_lshlrev_b64 v[168:169], 6, v[168:169]
	v_lshlrev_b64 v[170:171], 6, v[170:171]
	v_lshlrev_b64 v[176:177], 6, v[146:147]
	global_load_dwordx4 v[160:163], v[148:149], off
	s_nop 0
	global_load_dwordx4 v[164:167], v[164:165], off
	v_lshl_add_u64 v[168:169], v[138:139], 0, v[168:169]
	v_lshl_add_u64 v[172:173], v[138:139], 0, v[170:171]
	v_lshl_add_u64 v[176:177], v[138:139], 0, v[176:177]
	global_load_dwordx4 v[168:171], v[168:169], off
	s_nop 0
	global_load_dwordx4 v[172:175], v[172:173], off
	v_add_co_u32_e32 v148, vcc, s26, v148
	global_load_dwordx4 v[176:179], v[176:177], off
	s_nop 0
	v_addc_co_u32_e32 v149, vcc, 0, v149, vcc
	global_load_dwordx4 v[180:183], v[148:149], off offset:1024
	global_load_dwordx4 v[184:187], v[148:149], off offset:2048
	global_load_dwordx4 v[190:193], v[148:149], off offset:3072
	v_and_b32_e32 v147, 64, v156
	v_xor_b32_e32 v136, 16, v156
	v_add_u32_e32 v147, 64, v147
	v_xor_b32_e32 v149, 32, v156
	v_cmp_lt_i32_e32 vcc, v136, v147
	v_pk_mul_f32 v[120:121], v[124:125], v[120:121]
	v_pk_mul_f32 v[122:123], v[126:127], v[122:123]
	v_cndmask_b32_e32 v136, v156, v136, vcc
	v_cmp_lt_i32_e32 vcc, v149, v147
	v_lshlrev_b32_e32 v136, 2, v136
	v_pk_mul_f32 v[112:113], v[116:117], v[112:113]
	v_cndmask_b32_e32 v147, v156, v149, vcc
	v_lshlrev_b32_e32 v147, 2, v147
	v_pk_mul_f32 v[114:115], v[118:119], v[114:115]
	v_pk_mul_f32 v[104:105], v[108:109], v[104:105]
	s_ashr_i32 s3, s2, 13
	s_mul_hi_i32 s11, s3, 0x4400000
	s_mul_i32 s3, s3, 0x4400000
	v_readlane_b32 s16, v235, 44
	v_lshl_or_b32 v148, s42, 7, v152
	v_readlane_b32 s17, v235, 45
	v_pk_mul_f32 v[106:107], v[110:111], v[106:107]
	v_pk_mul_f32 v[96:97], v[100:101], v[96:97]
	v_pk_mul_f32 v[98:99], v[102:103], v[98:99]
	v_pk_mul_f32 v[88:89], v[92:93], v[88:89]
	v_pk_mul_f32 v[90:91], v[94:95], v[90:91]
	v_pk_mul_f32 v[80:81], v[84:85], v[80:81]
	v_pk_mul_f32 v[82:83], v[86:87], v[82:83]
	v_pk_mul_f32 v[72:73], v[76:77], v[72:73]
	v_pk_mul_f32 v[74:75], v[78:79], v[74:75]
	v_pk_mul_f32 v[64:65], v[68:69], v[64:65]
	v_pk_mul_f32 v[66:67], v[70:71], v[66:67]
	v_pk_mul_f32 v[56:57], v[60:61], v[56:57]
	v_pk_mul_f32 v[58:59], v[62:63], v[58:59]
	v_pk_mul_f32 v[48:49], v[52:53], v[48:49]
	v_pk_mul_f32 v[50:51], v[54:55], v[50:51]
	v_pk_mul_f32 v[40:41], v[44:45], v[40:41]
	v_pk_mul_f32 v[42:43], v[46:47], v[42:43]
	v_pk_mul_f32 v[32:33], v[36:37], v[32:33]
	v_pk_mul_f32 v[34:35], v[38:39], v[34:35]
	v_pk_mul_f32 v[24:25], v[28:29], v[24:25]
	v_pk_mul_f32 v[26:27], v[30:31], v[26:27]
	v_pk_mul_f32 v[16:17], v[20:21], v[16:17]
	v_pk_mul_f32 v[18:19], v[22:23], v[18:19]
	v_pk_mul_f32 v[8:9], v[12:13], v[8:9]
	v_pk_mul_f32 v[10:11], v[14:15], v[10:11]
	v_pk_mul_f32 v[0:1], v[4:5], v[0:1]
	v_pk_mul_f32 v[2:3], v[6:7], v[2:3]
	s_waitcnt vmcnt(0)
	v_mov_b32_e32 v194, v161
	v_mov_b32_e32 v195, v162
	v_mov_b32_e32 v161, v163
	v_pk_add_f32 v[160:161], v[194:195], v[160:161]
	v_mov_b32_e32 v162, v165
	v_mov_b32_e32 v163, v166
	v_mov_b32_e32 v165, v167
	v_mov_b32_e32 v166, v169
	v_mov_b32_e32 v167, v170
	v_mov_b32_e32 v169, v171
	v_mov_b32_e32 v170, v173
	v_mov_b32_e32 v171, v174
	v_mov_b32_e32 v173, v175
	v_mov_b32_e32 v174, v177
	v_mov_b32_e32 v175, v178
	v_mov_b32_e32 v177, v179
	v_add_f32_e32 v149, v160, v161
	v_pk_add_f32 v[160:161], v[162:163], v[164:165]
	v_pk_add_f32 v[162:163], v[166:167], v[168:169]
	v_pk_add_f32 v[166:167], v[174:175], v[176:177]
	v_add_f32_e32 v160, v160, v161
	v_add_f32_e32 v161, v162, v163
	v_mov_b32_e32 v236, v149
	v_mov_b32_e32 v237, v149
	s_nop 1
	v_permlane16_swap_b32_e32 v236, v237
	v_cndmask_b32_e64 v159, v237, v236, s[98:99]
	v_add_f32_e32 v163, v166, v167
	v_mov_b32_e32 v236, v160
	v_mov_b32_e32 v237, v160
	s_nop 1
	v_permlane16_swap_b32_e32 v236, v237
	v_cndmask_b32_e64 v166, v237, v236, s[98:99]
	v_mov_b32_e32 v236, v161
	v_mov_b32_e32 v237, v161
	s_nop 1
	v_permlane16_swap_b32_e32 v236, v237
	v_cndmask_b32_e64 v167, v237, v236, s[98:99]
	v_mov_b32_e32 v178, v181
	s_waitcnt lgkmcnt(2)
	v_add_f32_e32 v149, v149, v159
	v_mov_b32_e32 v236, v149
	v_mov_b32_e32 v237, v149
	s_nop 1
	v_permlane32_swap_b32_e32 v236, v237
	v_cndmask_b32_e64 v159, v237, v236, s[100:101]
	s_waitcnt lgkmcnt(2)
	v_add_f32_e32 v160, v160, v166
	s_waitcnt lgkmcnt(1)
	v_add_f32_e32 v161, v161, v167
	v_mov_b32_e32 v236, v160
	v_mov_b32_e32 v237, v160
	s_nop 1
	v_permlane32_swap_b32_e32 v236, v237
	v_cndmask_b32_e64 v166, v237, v236, s[100:101]
	v_mov_b32_e32 v236, v161
	v_mov_b32_e32 v237, v161
	s_nop 1
	v_permlane32_swap_b32_e32 v236, v237
	v_cndmask_b32_e64 v167, v237, v236, s[100:101]
	v_mov_b32_e32 v179, v182
	v_mov_b32_e32 v181, v183
	v_mov_b32_e32 v182, v185
	v_mov_b32_e32 v183, v186
	v_mov_b32_e32 v185, v187
	v_mov_b32_e32 v186, v191
	v_mov_b32_e32 v187, v192
	v_mov_b32_e32 v191, v193
	v_pk_add_f32 v[164:165], v[170:171], v[172:173]
	v_pk_add_f32 v[168:169], v[178:179], v[180:181]
	v_pk_add_f32 v[170:171], v[182:183], v[184:185]
	s_waitcnt lgkmcnt(2)
; template <int NP> __device__ __forceinline__ void load_rs(const float* ssp, int row0, int fq, float (&rs)[2][4]) {
;     ...
;             for (int m = 0; m < 4; ++m) { float s = (p[ai][m][0] + p[ai][m][1]) + (p[ai][m][2] + p[ai][m][3]); s += __shfl_xor(s, 16); s += __shfl_xor(s, 32); rs[ai][m] = s; }
;     }
; #pragma unroll
;     for (int ai = 0; ai < 2; ++ai)
; #pragma unroll
;         for (int m = 0; m < 4; ++m) rs[ai][m] = __builtin_amdgcn_rsqf(rs[ai][m] * (1.0f / D_MODEL) + RMS_EPS);
;     __device__ __forceinline__ void operator()(const f32x4 (&acc)[2][2][4][2], const Unit& u, int wr, int wc, int fr, int fq) const {
;     ...
;         float rs[2][4]; load_rs<NP>(ssp, row0, fq, rs);
; #pragma unroll
;         for (int ai = 0; ai < 2; ++ai)
; #pragma unroll
;             for (int m = 0; m < 4; ++m) {
;                 const int row = row0 + ai * HALF + m * 16; const float r = rs[ai][m];
;                 const float nrl = r * -1.44269504089f, r2 = r * r;
	v_add_f32_e32 v149, v149, v159
	s_waitcnt lgkmcnt(1)
	v_add_f32_e32 v159, v160, v166
	s_waitcnt lgkmcnt(0)
	v_add_f32_e32 v166, v161, v167
	v_pk_add_f32 v[160:161], v[186:187], v[190:191]
	v_add_f32_e32 v162, v164, v165
	v_add_f32_e32 v164, v168, v169
	v_add_f32_e32 v165, v170, v171
	v_add_f32_e32 v160, v160, v161
	v_mov_b32_e32 v236, v162
	v_mov_b32_e32 v237, v162
	s_nop 1
	v_permlane16_swap_b32_e32 v236, v237
	v_cndmask_b32_e64 v168, v237, v236, s[98:99]
	v_mov_b32_e32 v236, v163
	v_mov_b32_e32 v237, v163
	s_nop 1
	v_permlane16_swap_b32_e32 v236, v237
	v_cndmask_b32_e64 v169, v237, v236, s[98:99]
	v_mov_b32_e32 v236, v164
	v_mov_b32_e32 v237, v164
	s_nop 1
	v_permlane16_swap_b32_e32 v236, v237
	v_cndmask_b32_e64 v170, v237, v236, s[98:99]
	v_mov_b32_e32 v236, v165
	v_mov_b32_e32 v237, v165
	s_nop 1
	v_permlane16_swap_b32_e32 v236, v237
	v_cndmask_b32_e64 v171, v237, v236, s[98:99]
	v_mov_b32_e32 v236, v160
	v_mov_b32_e32 v237, v160
	s_nop 1
	v_permlane16_swap_b32_e32 v236, v237
	v_cndmask_b32_e64 v136, v237, v236, s[98:99]
	s_waitcnt lgkmcnt(4)
	v_add_f32_e32 v162, v162, v168
	s_waitcnt lgkmcnt(3)
	v_add_f32_e32 v163, v163, v169
	s_waitcnt lgkmcnt(2)
	v_add_f32_e32 v161, v164, v170
	s_waitcnt lgkmcnt(1)
	v_add_f32_e32 v165, v165, v171
	s_waitcnt lgkmcnt(0)
	v_add_f32_e32 v136, v160, v136
	v_mov_b32_e32 v236, v162
	v_mov_b32_e32 v237, v162
	s_nop 1
	v_permlane32_swap_b32_e32 v236, v237
	v_cndmask_b32_e64 v168, v237, v236, s[100:101]
	v_mov_b32_e32 v236, v163
	v_mov_b32_e32 v237, v163
	s_nop 1
	v_permlane32_swap_b32_e32 v236, v237
	v_cndmask_b32_e64 v169, v237, v236, s[100:101]
	v_mov_b32_e32 v236, v161
	v_mov_b32_e32 v237, v161
	s_nop 1
	v_permlane32_swap_b32_e32 v236, v237
	v_cndmask_b32_e64 v164, v237, v236, s[100:101]
	v_mov_b32_e32 v236, v165
	v_mov_b32_e32 v237, v165
	s_nop 1
	v_permlane32_swap_b32_e32 v236, v237
	v_cndmask_b32_e64 v167, v237, v236, s[100:101]
	v_mov_b32_e32 v236, v136
	v_mov_b32_e32 v237, v136
	s_nop 1
	v_permlane32_swap_b32_e32 v236, v237
	v_cndmask_b32_e64 v147, v237, v236, s[100:101]
	s_waitcnt lgkmcnt(4)
	v_add_f32_e32 v160, v162, v168
	s_waitcnt lgkmcnt(3)
	v_add_f32_e32 v162, v163, v169
	s_waitcnt lgkmcnt(2)
	v_add_f32_e32 v161, v161, v164
	s_waitcnt lgkmcnt(1)
	v_add_f32_e32 v163, v165, v167
	s_waitcnt lgkmcnt(0)
	v_add_f32_e32 v136, v136, v147
	v_fmamk_f32 v147, v149, 0x3a800000, v157
	v_rsq_f32_e32 v164, v147
	s_nop 0
	v_mov_b32_e32 v240, v164
	v_fmamk_f32 v147, v159, 0x3a800000, v157
	v_rsq_f32_e32 v165, v147
	s_nop 0
	v_mov_b32_e32 v241, v165
	v_fmamk_f32 v147, v166, 0x3a800000, v157
	v_rsq_f32_e32 v166, v147
	s_nop 0
	v_mov_b32_e32 v242, v166
	v_fmamk_f32 v147, v160, 0x3a800000, v157
	v_rsq_f32_e32 v167, v147
	s_nop 0
	v_mov_b32_e32 v243, v167
	v_fmamk_f32 v147, v162, 0x3a800000, v157
	v_rsq_f32_e32 v168, v147
	s_nop 0
	v_mov_b32_e32 v244, v168
	v_fmamk_f32 v147, v161, 0x3a800000, v157
	v_rsq_f32_e32 v160, v147
	s_nop 0
	v_mov_b32_e32 v245, v160
	v_fmamk_f32 v147, v163, 0x3a800000, v157
	v_fmamk_f32 v136, v136, 0x3a800000, v157
	v_rsq_f32_e32 v159, v147
	s_nop 0
	v_mov_b32_e32 v246, v159
	v_rsq_f32_e32 v147, v136
	s_nop 0
	v_mov_b32_e32 v247, v147
	v_mov_b32_e32 v248, s41
	s_branch rsc_join_1
rsc_hit_1:
	s_lshl_b32 s2, s41, 8
	s_add_i32 s2, s2, s29
	v_or_b32_e32 v146, s2, v150
	s_nop 4
	v_add_u32_e32 v146, 0x80, v146
	v_pk_mul_f32 v[120:121], v[124:125], v[120:121]
	v_pk_mul_f32 v[122:123], v[126:127], v[122:123]
	v_pk_mul_f32 v[112:113], v[116:117], v[112:113]
	v_pk_mul_f32 v[114:115], v[118:119], v[114:115]
	v_pk_mul_f32 v[104:105], v[108:109], v[104:105]
	s_ashr_i32 s3, s2, 13
	s_mul_hi_i32 s11, s3, 0x4400000
	s_mul_i32 s3, s3, 0x4400000
	v_readlane_b32 s16, v235, 44
	v_lshl_or_b32 v148, s42, 7, v152
	v_readlane_b32 s17, v235, 45
	v_pk_mul_f32 v[106:107], v[110:111], v[106:107]
	v_pk_mul_f32 v[96:97], v[100:101], v[96:97]
	v_pk_mul_f32 v[98:99], v[102:103], v[98:99]
	v_pk_mul_f32 v[88:89], v[92:93], v[88:89]
	v_pk_mul_f32 v[90:91], v[94:95], v[90:91]
	v_pk_mul_f32 v[80:81], v[84:85], v[80:81]
	v_pk_mul_f32 v[82:83], v[86:87], v[82:83]
	v_pk_mul_f32 v[72:73], v[76:77], v[72:73]
	v_pk_mul_f32 v[74:75], v[78:79], v[74:75]
	v_pk_mul_f32 v[64:65], v[68:69], v[64:65]
	v_pk_mul_f32 v[66:67], v[70:71], v[66:67]
	v_pk_mul_f32 v[56:57], v[60:61], v[56:57]
	v_pk_mul_f32 v[58:59], v[62:63], v[58:59]
	v_pk_mul_f32 v[48:49], v[52:53], v[48:49]
	v_pk_mul_f32 v[50:51], v[54:55], v[50:51]
	v_pk_mul_f32 v[40:41], v[44:45], v[40:41]
	v_pk_mul_f32 v[42:43], v[46:47], v[42:43]
	v_pk_mul_f32 v[32:33], v[36:37], v[32:33]
	v_pk_mul_f32 v[34:35], v[38:39], v[34:35]
	v_pk_mul_f32 v[24:25], v[28:29], v[24:25]
	v_pk_mul_f32 v[26:27], v[30:31], v[26:27]
	v_pk_mul_f32 v[16:17], v[20:21], v[16:17]
	v_pk_mul_f32 v[18:19], v[22:23], v[18:19]
	v_pk_mul_f32 v[8:9], v[12:13], v[8:9]
	v_pk_mul_f32 v[10:11], v[14:15], v[10:11]
	v_pk_mul_f32 v[0:1], v[4:5], v[0:1]
	v_pk_mul_f32 v[2:3], v[6:7], v[2:3]
	s_waitcnt vmcnt(0)
	v_mov_b32_e32 v164, v240
	v_mov_b32_e32 v165, v241
	v_mov_b32_e32 v166, v242
	v_mov_b32_e32 v167, v243
	v_mov_b32_e32 v168, v244
	v_mov_b32_e32 v160, v245
	v_mov_b32_e32 v159, v246
	v_mov_b32_e32 v147, v247
	s_waitcnt lgkmcnt(0)
